# 64-byte alignment of the hot loop heads; NA/dilated/GQA softmax: dropped self-max canonicalisations and 0+x; GQA SGPR-based K/V prefetch addressing and early first-PV-group V reads
# baseline (speedup 1.0000x reference)
; template <class Epi, class Sched>
; __device__ __forceinline__ void gemm_phase(LAS unsigned char* lds, const Gemm g, const Sched& S, const Epi& E, const int tid) {
;     ...
;         const bool has_next = S.next(ui + 1, nxt);
;         const char* nA = has_next ? (const char*)g.A + (size_t)nxt.pm * tstepA : cA; const char* nB = has_next ? (const char*)g.Bt + (size_t)nxt.pn * tstepB : cB;
;         for (int t = 0; t < nt; t += 2) {
;             const bool last = (t == nt - 2);
;             const char* a1 = cA + (size_t)(t + 1) * kstep;
;             const char* a2 = last ? nA : cA + (size_t)(t + 2) * kstep; const char* b2 = last ? nB : cB + (size_t)(t + 2) * kstep;
;     ...
; #pragma unroll
;         for (int a = 0; a < 2; ++a)
; #pragma unroll
;             for (int b = 0; b < 2; ++b)
; #pragma unroll
;                 for (int m = 0; m < 4; ++m)
; #pragma unroll
;                     for (int n = 0; n < 2; ++n) acc[a][b][m][n] = (f32x4){0.f, 0.f, 0.f, 0.f};
;         cur = nxt; cA = nA; cB = nB; ++ui;
.LBB0_141:
	s_ashr_i32 s41, s40, 31
	s_lshl_b64 s[2:3], s[40:41], 20
	s_add_u32 s2, s20, s2
	s_addc_u32 s3, s21, s3
	s_and_b64 s[42:43], s[36:37], exec
	s_cselect_b32 s15, s3, s45
	s_cselect_b32 s24, s2, s44
	s_ashr_i32 s39, s38, 31
	s_lshl_b64 s[42:43], s[38:39], 20
	s_add_u32 s42, s22, s42
	s_addc_u32 s43, s23, s43
	s_and_b64 s[48:49], s[36:37], exec
	s_cselect_b32 s26, s43, s47
	s_cselect_b32 s39, s42, s46
	s_add_u32 s44, s44, 0x80080
	s_addc_u32 s45, s45, 0
	s_add_u32 s41, s46, 0x100
	v_mov_b32_e32 v0, 0
	s_addc_u32 s58, s47, 0
	s_mov_b32 s59, -2
	v_mov_b32_e32 v1, v0
	v_mov_b32_e32 v2, v0
	v_mov_b32_e32 v3, v0
	v_mov_b32_e32 v4, v0
	v_mov_b32_e32 v5, v0
	v_mov_b32_e32 v6, v0
	v_mov_b32_e32 v7, v0
	v_mov_b32_e32 v8, v0
	v_mov_b32_e32 v9, v0
	v_mov_b32_e32 v10, v0
	v_mov_b32_e32 v11, v0
	v_mov_b32_e32 v12, v0
	v_mov_b32_e32 v13, v0
	v_mov_b32_e32 v14, v0
	v_mov_b32_e32 v15, v0
	v_mov_b32_e32 v24, v0
	v_mov_b32_e32 v25, v0
	v_mov_b32_e32 v26, v0
	v_mov_b32_e32 v27, v0
	v_mov_b32_e32 v28, v0
	v_mov_b32_e32 v29, v0
	v_mov_b32_e32 v30, v0
	v_mov_b32_e32 v31, v0
	v_mov_b32_e32 v40, v0
	v_mov_b32_e32 v41, v0
	v_mov_b32_e32 v42, v0
	v_mov_b32_e32 v43, v0
	v_mov_b32_e32 v44, v0
	v_mov_b32_e32 v45, v0
	v_mov_b32_e32 v46, v0
	v_mov_b32_e32 v47, v0
	v_mov_b32_e32 v16, v0
	v_mov_b32_e32 v17, v0
	v_mov_b32_e32 v18, v0
	v_mov_b32_e32 v19, v0
	v_mov_b32_e32 v20, v0
	v_mov_b32_e32 v21, v0
	v_mov_b32_e32 v22, v0
	v_mov_b32_e32 v23, v0
	v_mov_b32_e32 v32, v0
	v_mov_b32_e32 v33, v0
	v_mov_b32_e32 v34, v0
	v_mov_b32_e32 v35, v0
	v_mov_b32_e32 v36, v0
	v_mov_b32_e32 v37, v0
	v_mov_b32_e32 v38, v0
	v_mov_b32_e32 v39, v0
	v_mov_b32_e32 v48, v0
	v_mov_b32_e32 v49, v0
	v_mov_b32_e32 v50, v0
	v_mov_b32_e32 v51, v0
	v_mov_b32_e32 v52, v0
	v_mov_b32_e32 v53, v0
	v_mov_b32_e32 v54, v0
	v_mov_b32_e32 v55, v0
	v_mov_b32_e32 v56, v0
	v_mov_b32_e32 v57, v0
	v_mov_b32_e32 v58, v0
	v_mov_b32_e32 v59, v0
	v_mov_b32_e32 v60, v0
	v_mov_b32_e32 v61, v0
	v_mov_b32_e32 v62, v0
	v_mov_b32_e32 v63, v0
	v_mov_b32_e32 v64, v0
	v_mov_b32_e32 v65, v0
	v_mov_b32_e32 v66, v0
	v_mov_b32_e32 v67, v0
	v_mov_b32_e32 v68, v0
	v_mov_b32_e32 v69, v0
	v_mov_b32_e32 v70, v0
	v_mov_b32_e32 v71, v0
	v_mov_b32_e32 v72, v0
	v_mov_b32_e32 v73, v0
	v_mov_b32_e32 v74, v0
	v_mov_b32_e32 v75, v0
	v_mov_b32_e32 v76, v0
	v_mov_b32_e32 v77, v0
	v_mov_b32_e32 v78, v0
	v_mov_b32_e32 v79, v0
	v_mov_b32_e32 v88, v0
	v_mov_b32_e32 v89, v0
	v_mov_b32_e32 v90, v0
	v_mov_b32_e32 v91, v0
	v_mov_b32_e32 v92, v0
	v_mov_b32_e32 v93, v0
	v_mov_b32_e32 v94, v0
	v_mov_b32_e32 v95, v0
	v_mov_b32_e32 v104, v0
	v_mov_b32_e32 v105, v0
	v_mov_b32_e32 v106, v0
	v_mov_b32_e32 v107, v0
	v_mov_b32_e32 v108, v0
	v_mov_b32_e32 v109, v0
	v_mov_b32_e32 v110, v0
	v_mov_b32_e32 v111, v0
	v_mov_b32_e32 v80, v0
	v_mov_b32_e32 v81, v0
	v_mov_b32_e32 v82, v0
	v_mov_b32_e32 v83, v0
	v_mov_b32_e32 v84, v0
	v_mov_b32_e32 v85, v0
	v_mov_b32_e32 v86, v0
	v_mov_b32_e32 v87, v0
	v_mov_b32_e32 v96, v0
	v_mov_b32_e32 v97, v0
	v_mov_b32_e32 v98, v0
	v_mov_b32_e32 v99, v0
	v_mov_b32_e32 v100, v0
	v_mov_b32_e32 v101, v0
	v_mov_b32_e32 v102, v0
	v_mov_b32_e32 v103, v0
	v_mov_b32_e32 v112, v0
	v_mov_b32_e32 v113, v0
	v_mov_b32_e32 v114, v0
	v_mov_b32_e32 v115, v0
	v_mov_b32_e32 v116, v0
	v_mov_b32_e32 v117, v0
	v_mov_b32_e32 v118, v0
	v_mov_b32_e32 v119, v0
	v_mov_b32_e32 v120, v0
	v_mov_b32_e32 v121, v0
	v_mov_b32_e32 v122, v0
	v_mov_b32_e32 v123, v0
	v_mov_b32_e32 v124, v0
	v_mov_b32_e32 v125, v0
	v_mov_b32_e32 v126, v0
	v_mov_b32_e32 v127, v0
	.p2align	6

; #define PG8_STAGE(bufoff, gbase, voff) do { _Pragma("unroll") for (int _i = 0; _i < 2; ++_i) \
;         __builtin_amdgcn_global_load_lds((const unsigned*)((const char*)(gbase) + (voff)[_i]), (LAS unsigned*)(lds + (bufoff) + ldsw + _i * 8192), 16, 0, 0); } while (0)
; #define PG8_LDA(dst, b, h) do { _Pragma("unroll") for (int m = 0; m < 4; ++m) _Pragma("unroll") for (int k = 0; k < 2; ++k) dst[m][k] = *(const LAS bf16x8*)(lds + PG8_SA(b, h) + aoff + m * 2048 + k * 1024); } while (0)
; #define PG8_LDB(dst, b, h) do { _Pragma("unroll") for (int n = 0; n < 2; ++n) _Pragma("unroll") for (int k = 0; k < 2; ++k) dst[n][k] = *(const LAS bf16x8*)(lds + PG8_SB(b, h) + boff + n * 2048 + k * 1024); } while (0)
; #define PG8_MMA(ai, bj, At, Bt) do { __builtin_amdgcn_s_setprio(1); _Pragma("unroll") for (int m = 0; m < 4; ++m) _Pragma("unroll") for (int n = 0; n < 2; ++n) _Pragma("unroll") for (int k = 0; k < 2; ++k) \
;         acc[ai][bj][m][n] = __builtin_amdgcn_mfma_f32_16x16x32_bf16(Bt[n][k], At[m][k], acc[ai][bj][m][n], 0, 0, 0); __builtin_amdgcn_s_setprio(0); } while (0)
; #define PG8_WAIT_V(n) asm volatile("s_waitcnt vmcnt(" #n ")" ::: "memory")
; #define PG8_WAIT_L(n) asm volatile("s_waitcnt lgkmcnt(" #n ")" ::: "memory")
; #define PG8_BAR __builtin_amdgcn_s_barrier()
; #define PG8_SCHED __builtin_amdgcn_sched_barrier(0)
; template <class Epi, class Sched>
; __device__ __forceinline__ void gemm_phase(LAS unsigned char* lds, const Gemm g, const Sched& S, const Epi& E, const int tid) {
;     ...
;             PG8_LDB(B0, 0, 0); PG8_LDB(B1, 0, 1); PG8_SCHED; PG8_LDA(At, 0, 0); PG8_STAGE(PG8_SA(1, 1), a1 + hstepA, voffA);
;             PG8_WAIT_V(8); PG8_WAIT_L(0); PG8_BAR; PG8_MMA(0, 0, At, B0); PG8_MMA(0, 1, At, B1); PG8_BAR; PG8_SCHED;
;             PG8_LDA(At, 0, 1); PG8_STAGE(PG8_SB(0, 0), b2, voffB); PG8_STAGE(PG8_SB(0, 1), b2 + hstepB, voffB); PG8_STAGE(PG8_SA(0, 0), a2, voffA);
;             PG8_WAIT_V(8); PG8_WAIT_L(0); PG8_BAR; PG8_MMA(1, 0, At, B0); PG8_MMA(1, 1, At, B1); PG8_BAR; PG8_SCHED;
.LBB0_174:
	s_add_u32 s2, s40, s42
	s_addc_u32 s3, s41, s43
	s_add_u32 s2, s2, 0x100
	s_addc_u32 s3, s3, 0
	s_add_u32 s15, s20, s42
	s_addc_u32 s23, s21, s43
	s_cmpk_eq_i32 s42, 0x1300
	s_cselect_b32 s45, s1, s3
	s_cselect_b32 s44, s0, s2
	s_cselect_b32 s3, s39, s23
	s_cselect_b32 s2, s38, s15
	s_add_i32 s15, 0, 0x10000
	s_add_i32 s23, 0, 0x14000
	v_add_u32_e32 v140, s15, v235
	v_add_u32_e32 v156, s23, v235
	ds_read_b128 v[128:131], v140
	ds_read_b128 v[132:135], v140 offset:1024
	ds_read_b128 v[136:139], v140 offset:2048
	ds_read_b128 v[140:143], v140 offset:3072
	ds_read_b128 v[144:147], v156
	ds_read_b128 v[148:151], v156 offset:1024
	ds_read_b128 v[152:155], v156 offset:2048
	ds_read_b128 v[156:159], v156 offset:3072
	v_lshl_add_u64 v[216:217], v[212:213], 0, s[42:43]
	s_add_i32 m0, s50, 0xc000
	ds_read_b128 v[160:163], v236
	ds_read_b128 v[164:167], v236 offset:1024
	ds_read_b128 v[168:171], v236 offset:2048
	ds_read_b128 v[172:175], v236 offset:3072
	ds_read_b128 v[176:179], v236 offset:4096
	ds_read_b128 v[180:183], v236 offset:5120
	ds_read_b128 v[184:187], v236 offset:6144
	ds_read_b128 v[188:191], v236 offset:7168
	global_load_lds_dwordx4 v[216:217], off
	v_lshl_add_u64 v[216:217], v[214:215], 0, s[42:43]
	s_add_i32 m0, s50, 0xe000
	s_nop 0
	global_load_lds_dwordx4 v[216:217], off
	s_waitcnt vmcnt(8)
	s_waitcnt lgkmcnt(0)
	s_barrier
	s_setprio 1
	s_waitcnt lgkmcnt(0)
	v_mfma_f32_16x16x32_bf16 v[124:127], v[128:131], v[160:163], v[124:127]
	v_mfma_f32_16x16x32_bf16 v[120:123], v[136:139], v[160:163], v[120:123]
	v_mfma_f32_16x16x32_bf16 v[108:111], v[128:131], v[168:171], v[108:111]
	v_mfma_f32_16x16x32_bf16 v[104:107], v[136:139], v[168:171], v[104:107]
	v_mfma_f32_16x16x32_bf16 v[96:99], v[128:131], v[176:179], v[96:99]
	v_mfma_f32_16x16x32_bf16 v[88:91], v[136:139], v[176:179], v[88:91]
	v_mfma_f32_16x16x32_bf16 v[80:83], v[128:131], v[184:187], v[80:83]
	v_mfma_f32_16x16x32_bf16 v[72:75], v[136:139], v[184:187], v[72:75]
	v_mfma_f32_16x16x32_bf16 v[124:127], v[132:135], v[164:167], v[124:127]
	v_mfma_f32_16x16x32_bf16 v[120:123], v[140:143], v[164:167], v[120:123]
	v_mfma_f32_16x16x32_bf16 v[108:111], v[132:135], v[172:175], v[108:111]
	v_mfma_f32_16x16x32_bf16 v[104:107], v[140:143], v[172:175], v[104:107]
	v_mfma_f32_16x16x32_bf16 v[96:99], v[132:135], v[180:183], v[96:99]
	v_mfma_f32_16x16x32_bf16 v[88:91], v[140:143], v[180:183], v[88:91]
	v_mfma_f32_16x16x32_bf16 v[80:83], v[132:135], v[188:191], v[80:83]
	v_mfma_f32_16x16x32_bf16 v[72:75], v[140:143], v[188:191], v[72:75]
	s_setprio 0
	s_setprio 1
	v_mfma_f32_16x16x32_bf16 v[116:119], v[144:147], v[160:163], v[116:119]
	v_mfma_f32_16x16x32_bf16 v[112:115], v[152:155], v[160:163], v[112:115]
	v_mfma_f32_16x16x32_bf16 v[100:103], v[144:147], v[168:171], v[100:103]
	v_mfma_f32_16x16x32_bf16 v[92:95], v[152:155], v[168:171], v[92:95]
	v_mfma_f32_16x16x32_bf16 v[84:87], v[144:147], v[176:179], v[84:87]
	v_mfma_f32_16x16x32_bf16 v[76:79], v[152:155], v[176:179], v[76:79]
	v_mfma_f32_16x16x32_bf16 v[68:71], v[144:147], v[184:187], v[68:71]
	v_mfma_f32_16x16x32_bf16 v[64:67], v[152:155], v[184:187], v[64:67]
	v_mfma_f32_16x16x32_bf16 v[116:119], v[148:151], v[164:167], v[116:119]
	v_mfma_f32_16x16x32_bf16 v[112:115], v[156:159], v[164:167], v[112:115]
	v_mfma_f32_16x16x32_bf16 v[100:103], v[148:151], v[172:175], v[100:103]
	v_mfma_f32_16x16x32_bf16 v[92:95], v[156:159], v[172:175], v[92:95]
	v_mfma_f32_16x16x32_bf16 v[84:87], v[148:151], v[180:183], v[84:87]
	v_mfma_f32_16x16x32_bf16 v[76:79], v[156:159], v[180:183], v[76:79]
	v_mfma_f32_16x16x32_bf16 v[68:71], v[148:151], v[188:191], v[68:71]
	v_mfma_f32_16x16x32_bf16 v[64:67], v[156:159], v[188:191], v[64:67]
	s_setprio 0
	s_barrier
	s_add_i32 s15, s15, s49
	v_lshl_add_u64 v[216:217], s[2:3], 0, v[192:193]
	s_mov_b32 m0, s15
	ds_read_b128 v[160:163], v236 offset:16384
	ds_read_b128 v[164:167], v236 offset:17408
	ds_read_b128 v[168:171], v236 offset:18432
	ds_read_b128 v[172:175], v236 offset:19456
	ds_read_b128 v[176:179], v236 offset:20480
	ds_read_b128 v[180:183], v236 offset:21504
	ds_read_b128 v[184:187], v236 offset:22528
	ds_read_b128 v[188:191], v236 offset:23552
	global_load_lds_dwordx4 v[216:217], off
	s_add_i32 m0, s15, 0x2000
	s_add_u32 s66, s2, 0xa0000
	v_lshl_add_u64 v[218:219], s[2:3], 0, v[206:207]
	s_addc_u32 s67, s3, 0
	s_add_i32 s15, s23, s49
	global_load_lds_dwordx4 v[218:219], off
	v_lshl_add_u64 v[220:221], s[66:67], 0, v[192:193]
	s_mov_b32 m0, s15
	v_lshl_add_u64 v[222:223], s[44:45], 0, v[204:205]
	global_load_lds_dwordx4 v[220:221], off
	v_lshl_add_u64 v[220:221], s[66:67], 0, v[206:207]
	s_add_i32 m0, s15, 0x2000
	s_nop 0
	global_load_lds_dwordx4 v[220:221], off
	v_lshl_add_u64 v[220:221], s[44:45], 0, v[202:203]
	s_mov_b32 m0, s50
	s_nop 0
	global_load_lds_dwordx4 v[220:221], off
	s_mov_b32 m0, s51
	s_nop 0
	global_load_lds_dwordx4 v[222:223], off
	s_waitcnt vmcnt(8)
	s_waitcnt lgkmcnt(0)
	s_barrier
; #define PG8_STAGE(bufoff, gbase, voff) do { _Pragma("unroll") for (int _i = 0; _i < 2; ++_i) \
;         __builtin_amdgcn_global_load_lds((const unsigned*)((const char*)(gbase) + (voff)[_i]), (LAS unsigned*)(lds + (bufoff) + ldsw + _i * 8192), 16, 0, 0); } while (0)
; #define PG8_LDA(dst, b, h) do { _Pragma("unroll") for (int m = 0; m < 4; ++m) _Pragma("unroll") for (int k = 0; k < 2; ++k) dst[m][k] = *(const LAS bf16x8*)(lds + PG8_SA(b, h) + aoff + m * 2048 + k * 1024); } while (0)
; #define PG8_LDB(dst, b, h) do { _Pragma("unroll") for (int n = 0; n < 2; ++n) _Pragma("unroll") for (int k = 0; k < 2; ++k) dst[n][k] = *(const LAS bf16x8*)(lds + PG8_SB(b, h) + boff + n * 2048 + k * 1024); } while (0)
; #define PG8_MMA(ai, bj, At, Bt) do { __builtin_amdgcn_s_setprio(1); _Pragma("unroll") for (int m = 0; m < 4; ++m) _Pragma("unroll") for (int n = 0; n < 2; ++n) _Pragma("unroll") for (int k = 0; k < 2; ++k) \
;         acc[ai][bj][m][n] = __builtin_amdgcn_mfma_f32_16x16x32_bf16(Bt[n][k], At[m][k], acc[ai][bj][m][n], 0, 0, 0); __builtin_amdgcn_s_setprio(0); } while (0)
; #define PG8_WAIT_V(n) asm volatile("s_waitcnt vmcnt(" #n ")" ::: "memory")
; #define PG8_WAIT_L(n) asm volatile("s_waitcnt lgkmcnt(" #n ")" ::: "memory")
; #define PG8_BAR __builtin_amdgcn_s_barrier()
; #define PG8_SCHED __builtin_amdgcn_sched_barrier(0)
; template <class Epi, class Sched>
; __device__ __forceinline__ void gemm_phase(LAS unsigned char* lds, const Gemm g, const Sched& S, const Epi& E, const int tid) {
;     ...
;             PG8_WAIT_V(8); PG8_WAIT_L(0); PG8_BAR; PG8_MMA(1, 0, At, B0); PG8_MMA(1, 1, At, B1); PG8_BAR; PG8_SCHED;
;             PG8_LDB(B0, 1, 0); PG8_LDB(B1, 1, 1); PG8_SCHED; PG8_LDA(At, 1, 0); PG8_STAGE(PG8_SA(0, 1), a2 + hstepA, voffA);
;             PG8_WAIT_V(8); PG8_WAIT_L(0); PG8_BAR; PG8_MMA(0, 0, At, B0); PG8_MMA(0, 1, At, B1); PG8_BAR; PG8_SCHED;
;             PG8_LDA(At, 1, 1); PG8_STAGE(PG8_SB(1, 0), b3, voffB); PG8_STAGE(PG8_SB(1, 1), b3 + hstepB, voffB); PG8_STAGE(PG8_SA(1, 0), a3, voffA);
;             PG8_WAIT_V(8); PG8_WAIT_L(0); PG8_BAR; PG8_MMA(1, 0, At, B0); PG8_MMA(1, 1, At, B1); PG8_BAR; PG8_SCHED;
	s_setprio 1
	s_waitcnt lgkmcnt(0)
	v_mfma_f32_16x16x32_bf16 v[60:63], v[128:131], v[160:163], v[60:63]
	v_mfma_f32_16x16x32_bf16 v[56:59], v[136:139], v[160:163], v[56:59]
	v_mfma_f32_16x16x32_bf16 v[48:51], v[128:131], v[168:171], v[48:51]
	v_mfma_f32_16x16x32_bf16 v[40:43], v[136:139], v[168:171], v[40:43]
	v_mfma_f32_16x16x32_bf16 v[32:35], v[128:131], v[176:179], v[32:35]
	v_mfma_f32_16x16x32_bf16 v[24:27], v[136:139], v[176:179], v[24:27]
	v_mfma_f32_16x16x32_bf16 v[16:19], v[128:131], v[184:187], v[16:19]
	v_mfma_f32_16x16x32_bf16 v[8:11], v[136:139], v[184:187], v[8:11]
	v_mfma_f32_16x16x32_bf16 v[60:63], v[132:135], v[164:167], v[60:63]
	v_mfma_f32_16x16x32_bf16 v[56:59], v[140:143], v[164:167], v[56:59]
	v_mfma_f32_16x16x32_bf16 v[48:51], v[132:135], v[172:175], v[48:51]
	v_mfma_f32_16x16x32_bf16 v[40:43], v[140:143], v[172:175], v[40:43]
	v_mfma_f32_16x16x32_bf16 v[32:35], v[132:135], v[180:183], v[32:35]
	v_mfma_f32_16x16x32_bf16 v[24:27], v[140:143], v[180:183], v[24:27]
	v_mfma_f32_16x16x32_bf16 v[16:19], v[132:135], v[188:191], v[16:19]
	v_mfma_f32_16x16x32_bf16 v[8:11], v[140:143], v[188:191], v[8:11]
	s_setprio 0
	s_setprio 1
	v_mfma_f32_16x16x32_bf16 v[52:55], v[144:147], v[160:163], v[52:55]
	v_mfma_f32_16x16x32_bf16 v[44:47], v[152:155], v[160:163], v[44:47]
	v_mfma_f32_16x16x32_bf16 v[36:39], v[144:147], v[168:171], v[36:39]
	v_mfma_f32_16x16x32_bf16 v[28:31], v[152:155], v[168:171], v[28:31]
	v_mfma_f32_16x16x32_bf16 v[20:23], v[144:147], v[176:179], v[20:23]
	v_mfma_f32_16x16x32_bf16 v[12:15], v[152:155], v[176:179], v[12:15]
	v_mfma_f32_16x16x32_bf16 v[4:7], v[144:147], v[184:187], v[4:7]
	v_mfma_f32_16x16x32_bf16 v[0:3], v[152:155], v[184:187], v[0:3]
	v_mfma_f32_16x16x32_bf16 v[52:55], v[148:151], v[164:167], v[52:55]
	v_mfma_f32_16x16x32_bf16 v[44:47], v[156:159], v[164:167], v[44:47]
	v_mfma_f32_16x16x32_bf16 v[36:39], v[148:151], v[172:175], v[36:39]
	v_mfma_f32_16x16x32_bf16 v[28:31], v[156:159], v[172:175], v[28:31]
	v_mfma_f32_16x16x32_bf16 v[20:23], v[148:151], v[180:183], v[20:23]
	v_mfma_f32_16x16x32_bf16 v[12:15], v[156:159], v[180:183], v[12:15]
	v_mfma_f32_16x16x32_bf16 v[4:7], v[148:151], v[188:191], v[4:7]
	v_mfma_f32_16x16x32_bf16 v[0:3], v[156:159], v[188:191], v[0:3]
	s_setprio 0
	s_barrier
	s_add_i32 s15, 0, 0x18000
	s_add_i32 s23, 0, 0x1c000
	v_add_u32_e32 v140, s15, v235
	v_add_u32_e32 v156, s23, v235
	ds_read_b128 v[128:131], v140
	ds_read_b128 v[132:135], v140 offset:1024
	ds_read_b128 v[136:139], v140 offset:2048
	ds_read_b128 v[140:143], v140 offset:3072
	ds_read_b128 v[144:147], v156
	ds_read_b128 v[148:151], v156 offset:1024
	ds_read_b128 v[152:155], v156 offset:2048
	ds_read_b128 v[156:159], v156 offset:3072
	s_add_u32 s44, s44, 0xa0000
	s_addc_u32 s45, s45, 0
	s_mov_b32 m0, s52
	v_lshl_add_u64 v[238:239], s[44:45], 0, v[202:203]
	ds_read_b128 v[160:163], v236 offset:32768
	ds_read_b128 v[164:167], v236 offset:33792
	ds_read_b128 v[168:171], v236 offset:34816
	ds_read_b128 v[172:175], v236 offset:35840
	ds_read_b128 v[176:179], v236 offset:36864
	ds_read_b128 v[180:183], v236 offset:37888
	ds_read_b128 v[184:187], v236 offset:38912
	ds_read_b128 v[188:191], v236 offset:39936
	global_load_lds_dwordx4 v[238:239], off
	v_lshl_add_u64 v[238:239], s[44:45], 0, v[204:205]
	s_mov_b32 m0, s53
	s_nop 0
	global_load_lds_dwordx4 v[238:239], off
	s_waitcnt vmcnt(8)
	s_waitcnt lgkmcnt(0)
	s_barrier
	s_setprio 1
	s_waitcnt lgkmcnt(0)
	v_mfma_f32_16x16x32_bf16 v[124:127], v[128:131], v[160:163], v[124:127]
	v_mfma_f32_16x16x32_bf16 v[120:123], v[136:139], v[160:163], v[120:123]
	v_mfma_f32_16x16x32_bf16 v[108:111], v[128:131], v[168:171], v[108:111]
	v_mfma_f32_16x16x32_bf16 v[104:107], v[136:139], v[168:171], v[104:107]
	v_mfma_f32_16x16x32_bf16 v[96:99], v[128:131], v[176:179], v[96:99]
	v_mfma_f32_16x16x32_bf16 v[88:91], v[136:139], v[176:179], v[88:91]
	v_mfma_f32_16x16x32_bf16 v[80:83], v[128:131], v[184:187], v[80:83]
	v_mfma_f32_16x16x32_bf16 v[72:75], v[136:139], v[184:187], v[72:75]
	v_mfma_f32_16x16x32_bf16 v[124:127], v[132:135], v[164:167], v[124:127]
	v_mfma_f32_16x16x32_bf16 v[120:123], v[140:143], v[164:167], v[120:123]
	v_mfma_f32_16x16x32_bf16 v[108:111], v[132:135], v[172:175], v[108:111]
	v_mfma_f32_16x16x32_bf16 v[104:107], v[140:143], v[172:175], v[104:107]
	v_mfma_f32_16x16x32_bf16 v[96:99], v[132:135], v[180:183], v[96:99]
	v_mfma_f32_16x16x32_bf16 v[88:91], v[140:143], v[180:183], v[88:91]
	v_mfma_f32_16x16x32_bf16 v[80:83], v[132:135], v[188:191], v[80:83]
	v_mfma_f32_16x16x32_bf16 v[72:75], v[140:143], v[188:191], v[72:75]
	s_setprio 0
	s_setprio 1
	v_mfma_f32_16x16x32_bf16 v[116:119], v[144:147], v[160:163], v[116:119]
	v_mfma_f32_16x16x32_bf16 v[112:115], v[152:155], v[160:163], v[112:115]
	v_mfma_f32_16x16x32_bf16 v[100:103], v[144:147], v[168:171], v[100:103]
	v_mfma_f32_16x16x32_bf16 v[92:95], v[152:155], v[168:171], v[92:95]
	v_mfma_f32_16x16x32_bf16 v[84:87], v[144:147], v[176:179], v[84:87]
	v_mfma_f32_16x16x32_bf16 v[76:79], v[152:155], v[176:179], v[76:79]
	v_mfma_f32_16x16x32_bf16 v[68:71], v[144:147], v[184:187], v[68:71]
	v_mfma_f32_16x16x32_bf16 v[64:67], v[152:155], v[184:187], v[64:67]
	v_mfma_f32_16x16x32_bf16 v[116:119], v[148:151], v[164:167], v[116:119]
	v_mfma_f32_16x16x32_bf16 v[112:115], v[156:159], v[164:167], v[112:115]
	v_mfma_f32_16x16x32_bf16 v[100:103], v[148:151], v[172:175], v[100:103]
	v_mfma_f32_16x16x32_bf16 v[92:95], v[156:159], v[172:175], v[92:95]
	v_mfma_f32_16x16x32_bf16 v[84:87], v[148:151], v[180:183], v[84:87]
	v_mfma_f32_16x16x32_bf16 v[76:79], v[156:159], v[180:183], v[76:79]
	v_mfma_f32_16x16x32_bf16 v[68:71], v[148:151], v[188:191], v[68:71]
	v_mfma_f32_16x16x32_bf16 v[64:67], v[156:159], v[188:191], v[64:67]
	s_setprio 0
	s_barrier
; #define PG8_STAGE(bufoff, gbase, voff) do { _Pragma("unroll") for (int _i = 0; _i < 2; ++_i) \
;         __builtin_amdgcn_global_load_lds((const unsigned*)((const char*)(gbase) + (voff)[_i]), (LAS unsigned*)(lds + (bufoff) + ldsw + _i * 8192), 16, 0, 0); } while (0)
; #define PG8_LDA(dst, b, h) do { _Pragma("unroll") for (int m = 0; m < 4; ++m) _Pragma("unroll") for (int k = 0; k < 2; ++k) dst[m][k] = *(const LAS bf16x8*)(lds + PG8_SA(b, h) + aoff + m * 2048 + k * 1024); } while (0)
; #define PG8_MMA(ai, bj, At, Bt) do { __builtin_amdgcn_s_setprio(1); _Pragma("unroll") for (int m = 0; m < 4; ++m) _Pragma("unroll") for (int n = 0; n < 2; ++n) _Pragma("unroll") for (int k = 0; k < 2; ++k) \
;         acc[ai][bj][m][n] = __builtin_amdgcn_mfma_f32_16x16x32_bf16(Bt[n][k], At[m][k], acc[ai][bj][m][n], 0, 0, 0); __builtin_amdgcn_s_setprio(0); } while (0)
; #define PG8_WAIT_V(n) asm volatile("s_waitcnt vmcnt(" #n ")" ::: "memory")
; #define PG8_WAIT_L(n) asm volatile("s_waitcnt lgkmcnt(" #n ")" ::: "memory")
; #define PG8_BAR __builtin_amdgcn_s_barrier()
; #define PG8_SCHED __builtin_amdgcn_sched_barrier(0)
; template <class Epi, class Sched>
; __device__ __forceinline__ void gemm_phase(LAS unsigned char* lds, const Gemm g, const Sched& S, const Epi& E, const int tid) {
;     ...
;             PG8_WAIT_V(8); PG8_WAIT_L(0); PG8_BAR; PG8_MMA(0, 0, At, B0); PG8_MMA(0, 1, At, B1); PG8_BAR; PG8_SCHED;
;             PG8_LDA(At, 1, 1); PG8_STAGE(PG8_SB(1, 0), b3, voffB); PG8_STAGE(PG8_SB(1, 1), b3 + hstepB, voffB); PG8_STAGE(PG8_SA(1, 0), a3, voffA);
;             PG8_WAIT_V(8); PG8_WAIT_L(0); PG8_BAR; PG8_MMA(1, 0, At, B0); PG8_MMA(1, 1, At, B1); PG8_BAR; PG8_SCHED;
;         }
	s_add_i32 s15, s15, s49
	v_lshl_add_u64 v[216:217], v[216:217], 0, s[34:35]
	s_mov_b32 m0, s15
	ds_read_b128 v[160:163], v236 offset:49152
	ds_read_b128 v[164:167], v236 offset:50176
	ds_read_b128 v[168:171], v236 offset:51200
	ds_read_b128 v[172:175], v236 offset:52224
	ds_read_b128 v[176:179], v236 offset:53248
	ds_read_b128 v[180:183], v236 offset:54272
	ds_read_b128 v[184:187], v236 offset:55296
	ds_read_b128 v[188:191], v236 offset:56320
	global_load_lds_dwordx4 v[216:217], off
	s_add_i32 m0, s15, 0x2000
	s_add_u32 s2, s2, 0xa0080
	v_lshl_add_u64 v[216:217], v[218:219], 0, s[34:35]
	s_addc_u32 s3, s3, 0
	s_add_i32 s15, s23, s49
	global_load_lds_dwordx4 v[216:217], off
	v_lshl_add_u64 v[216:217], s[2:3], 0, v[192:193]
	s_mov_b32 m0, s15
	s_nop 0
	global_load_lds_dwordx4 v[216:217], off
	v_lshl_add_u64 v[216:217], s[2:3], 0, v[206:207]
	s_add_i32 m0, s15, 0x2000
	s_nop 0
	global_load_lds_dwordx4 v[216:217], off
	v_lshl_add_u64 v[216:217], v[220:221], 0, s[34:35]
	s_mov_b32 m0, s56
	s_nop 0
	global_load_lds_dwordx4 v[216:217], off
	v_lshl_add_u64 v[216:217], v[222:223], 0, s[34:35]
	s_mov_b32 m0, s57
	s_nop 0
	global_load_lds_dwordx4 v[216:217], off
	s_waitcnt vmcnt(8)
	s_waitcnt lgkmcnt(0)
	s_barrier
	s_setprio 1
	s_waitcnt lgkmcnt(0)
	v_mfma_f32_16x16x32_bf16 v[60:63], v[128:131], v[160:163], v[60:63]
	v_mfma_f32_16x16x32_bf16 v[56:59], v[136:139], v[160:163], v[56:59]
	v_mfma_f32_16x16x32_bf16 v[48:51], v[128:131], v[168:171], v[48:51]
	v_mfma_f32_16x16x32_bf16 v[40:43], v[136:139], v[168:171], v[40:43]
	v_mfma_f32_16x16x32_bf16 v[32:35], v[128:131], v[176:179], v[32:35]
	v_mfma_f32_16x16x32_bf16 v[24:27], v[136:139], v[176:179], v[24:27]
	v_mfma_f32_16x16x32_bf16 v[16:19], v[128:131], v[184:187], v[16:19]
	v_mfma_f32_16x16x32_bf16 v[8:11], v[136:139], v[184:187], v[8:11]
	v_mfma_f32_16x16x32_bf16 v[60:63], v[132:135], v[164:167], v[60:63]
	v_mfma_f32_16x16x32_bf16 v[56:59], v[140:143], v[164:167], v[56:59]
	v_mfma_f32_16x16x32_bf16 v[48:51], v[132:135], v[172:175], v[48:51]
	v_mfma_f32_16x16x32_bf16 v[40:43], v[140:143], v[172:175], v[40:43]
	v_mfma_f32_16x16x32_bf16 v[32:35], v[132:135], v[180:183], v[32:35]
	v_mfma_f32_16x16x32_bf16 v[24:27], v[140:143], v[180:183], v[24:27]
	v_mfma_f32_16x16x32_bf16 v[16:19], v[132:135], v[188:191], v[16:19]
	v_mfma_f32_16x16x32_bf16 v[8:11], v[140:143], v[188:191], v[8:11]
	s_setprio 0
	s_setprio 1
	v_mfma_f32_16x16x32_bf16 v[52:55], v[144:147], v[160:163], v[52:55]
	v_mfma_f32_16x16x32_bf16 v[44:47], v[152:155], v[160:163], v[44:47]
	v_mfma_f32_16x16x32_bf16 v[36:39], v[144:147], v[168:171], v[36:39]
	v_mfma_f32_16x16x32_bf16 v[28:31], v[152:155], v[168:171], v[28:31]
	v_mfma_f32_16x16x32_bf16 v[20:23], v[144:147], v[176:179], v[20:23]
	v_mfma_f32_16x16x32_bf16 v[12:15], v[152:155], v[176:179], v[12:15]
	v_mfma_f32_16x16x32_bf16 v[4:7], v[144:147], v[184:187], v[4:7]
	v_mfma_f32_16x16x32_bf16 v[0:3], v[152:155], v[184:187], v[0:3]
	v_mfma_f32_16x16x32_bf16 v[52:55], v[148:151], v[164:167], v[52:55]
	v_mfma_f32_16x16x32_bf16 v[44:47], v[156:159], v[164:167], v[44:47]
	v_mfma_f32_16x16x32_bf16 v[36:39], v[148:151], v[172:175], v[36:39]
	v_mfma_f32_16x16x32_bf16 v[28:31], v[156:159], v[172:175], v[28:31]
	v_mfma_f32_16x16x32_bf16 v[20:23], v[148:151], v[180:183], v[20:23]
	v_mfma_f32_16x16x32_bf16 v[12:15], v[156:159], v[180:183], v[12:15]
	v_mfma_f32_16x16x32_bf16 v[4:7], v[148:151], v[188:191], v[4:7]
	v_mfma_f32_16x16x32_bf16 v[0:3], v[156:159], v[188:191], v[0:3]
	s_setprio 0
	s_barrier
	s_add_i32 s2, s22, 2
	s_add_u32 s42, s42, 0x100
	s_addc_u32 s43, s43, 0
	s_cmp_gt_u32 s22, 37
	s_mov_b32 s22, s2
	s_cbranch_scc1 .LBB0_181
	.p2align	6

; #define SBAR() __builtin_amdgcn_sched_barrier(0)
; template <int MODE, int SDEPTH, bool SIMPLE>
; __device__ __forceinline__ void attn_body(const Unit& U, char* lds, const int tid) {
;     ...
;   const bf16_t* Qw = U.Q + (long)(wid * QBLK + r32) * U.ldq + hi * 8;
; #pragma unroll
;   for (int d0 = 0; d0 < 8; ++d0) qr[d0] = *reinterpret_cast<const bf16x8*>(Qw + d0 * 16);
;   const int sr = tid >> 4, sc = (tid & 15) * 8, vst0 = v_st(sr, sc), vst1 = v_st(32 + sr, sc);
;   const int vb0 = (int)(uintptr_t)V_lds + v_rd_base(lane);
;   const bf16_t* Kh = U.K; const bf16_t* Vh = U.V; const int LDK = U.ldk;
;   struct { bf16x8 vs0, vs1, ks0, ks1; } sr_[SDEPTH];
;     ...
;   bf16x8 pa0, pa1, pa2, pa3; const int NT = U.NT;
;   if constexpr (SIMPLE) {
;     f32x16 p0, p1; float mn, al;
;     SLOAD(0, 0);
;     for (int j = 0; j < NT; ++j) {
;       asm volatile("s_waitcnt vmcnt(0)" ::: "memory"); __syncthreads(); SWRITE(0, 0);
;       if (j + 1 < NT) SLOAD(0, (j + 1) * KVBLK);
;       __syncthreads();
;       bool act = true;
;       if constexpr (MODE == 1) { const int qrow = U.qr + (wid >> 1), kr = U.kr0 + j, st = min(max(qrow - 4, 0), 120); act = (kr >= st) && (kr < st + 8); }
;       if constexpr (MODE == 2) { const int q0 = U.i0 + wid * 32, t0 = U.k0 + j * 64; act = (t0 + 63 >= q0 - 64) && (t0 <= q0 + 31 + 64); }
;       if (act) {
;         qkt(p0, p1, K_lds, qr, r32, hi); amask<MODE>(p0, p1, j, U, wid, r32, hi, tbl);
;         partialSM(p0, p1, m_reg, mn, al); finishSM(p0, p1, al, l_reg, pa0, pa1, pa2, pa3);
;         RESC(al); SBAR();
;         pv_d0(o, vb0, pa0, pa1, pa2, pa3);
;       }
;     }
;   } else {
;   f32x16 pA0, pA1, pB0, pB1; float mnA, mnB, alA, alB;
;   constexpr int SE = 0, SO = SDEPTH - 1;
;   SLOAD(SE, 0); asm volatile("s_waitcnt vmcnt(0)" ::: "memory"); SWRITE(0, SE); __syncthreads();
; __global__ void __launch_bounds__(512) mega(Args a) {
;     ...
;         const int un = i * G + cu; if (un >= NB * 8 * 32) break;
;         const int h = un & 7, qb = (un >> 3) & 31, b = un >> 8;
;         __syncthreads();
;         att::Unit U{};
;         const size_t tq = (size_t)b * SEQ + qb * 256;
;         U.Q = QBc + ((size_t)(b * 8 + h) * SEQ + qb * 256) * 128; U.K = KBc + (size_t)(b * 2 + (h >> 2)) * SEQ * 128; U.V = VBc + (size_t)(b * 2 + (h >> 2)) * SEQ * 128;
;         U.ldq = 128; U.ldk = 128; U.NT = SEQ / 64;
.LBB0_198:
	s_ashr_i32 s30, s0, 8
	s_lshl_b32 s1, s0, 5
	s_and_b32 s16, s0, 7
	s_and_b32 s19, s1, 0x1f00
	s_lshl_b32 s1, s30, 3
	s_or_b32 s2, s1, s16
	s_ashr_i32 s3, s2, 31
	s_bfe_u32 s15, s28, 0x10002
	s_lshl_b64 s[2:3], s[2:3], 21
	s_add_u32 s1, s17, s2
	s_addc_u32 s2, s25, s3
	s_lshl_b32 s3, s19, 8
	s_add_u32 s36, s1, s3
	s_addc_u32 s37, s2, 0
	s_lshl_b32 s21, s30, 1
	s_bfe_u32 s0, s0, 0x10002
	s_or_b32 s0, s21, s0
	s_ashr_i32 s1, s0, 31
	s_waitcnt vmcnt(0)
	v_mov_b32_e32 v52, v177
	s_barrier
	s_lshl_b64 s[2:3], s[0:1], 21
	s_add_u32 s0, s58, s2
	v_ashrrev_i32_e32 v16, 4, v52
	v_lshlrev_b32_e32 v22, 3, v52
	v_add_u32_e32 v18, 32, v16
	s_addc_u32 s1, s59, s3
	v_and_b32_e32 v176, 0x78, v22
	v_ashrrev_i32_e32 v17, 31, v16
	v_ashrrev_i32_e32 v19, 31, v18
	s_add_u32 s2, s60, s2
	v_lshlrev_b32_e32 v23, 1, v176
	v_lshlrev_b64 v[48:49], 8, v[16:17]
	v_lshlrev_b64 v[12:13], 8, v[18:19]
	s_addc_u32 s3, s61, s3
	v_or_b32_e32 v50, v48, v23
	v_mov_b32_e32 v51, v49
	v_or_b32_e32 v12, v12, v23
	v_lshl_add_u64 v[0:1], s[2:3], 0, v[50:51]
	v_lshl_add_u64 v[4:5], s[2:3], 0, v[12:13]
	global_load_dwordx4 v[0:3], v[0:1], off
	s_nop 0
	global_load_dwordx4 v[4:7], v[4:5], off
	v_lshl_add_u64 v[8:9], s[0:1], 0, v[50:51]
	v_ashrrev_i32_e32 v184, 6, v52
	global_load_dwordx4 v[8:11], v[8:9], off
	v_lshl_add_u64 v[12:13], s[0:1], 0, v[12:13]
	v_and_b32_e32 v183, 31, v52
	v_lshlrev_b32_e32 v180, 5, v184
	global_load_dwordx4 v[12:15], v[12:13], off
	v_or_b32_e32 v20, v180, v183
	v_ashrrev_i32_e32 v21, 31, v20
	v_bfe_u32 v182, v52, 5, 1
	v_lshlrev_b64 v[20:21], 8, v[20:21]
	v_lshl_add_u64 v[20:21], s[36:37], 0, v[20:21]
	v_lshlrev_b32_e32 v192, 4, v182
	v_lshl_add_u64 v[20:21], v[20:21], 0, v[192:193]
	global_load_dwordx4 v[116:119], v[20:21], off
	global_load_dwordx4 v[112:115], v[20:21], off offset:32
	global_load_dwordx4 v[124:127], v[20:21], off offset:64
	global_load_dwordx4 v[120:123], v[20:21], off offset:96
	global_load_dwordx4 v[108:111], v[20:21], off offset:128
	global_load_dwordx4 v[104:107], v[20:21], off offset:160
	global_load_dwordx4 v[100:103], v[20:21], off offset:192
	global_load_dwordx4 v[96:99], v[20:21], off offset:224
	v_and_b32_e32 v19, 0xfffff0, v16
	v_lshlrev_b32_e32 v24, 1, v16
	v_lshrrev_b32_e32 v25, 1, v16
	v_and_b32_e32 v26, 3, v16
	v_and_or_b32 v19, v24, 8, v19
	v_and_or_b32 v24, v25, 4, v26
	v_and_b32_e32 v25, 0xfffff0, v18
	v_lshlrev_b32_e32 v26, 1, v18
	v_and_b32_e32 v17, 0x70, v52
	v_bfe_u32 v22, v22, 5, 2
	v_lshlrev_b32_e32 v16, 8, v16
	v_lshrrev_b32_e32 v19, 1, v19
	v_and_or_b32 v25, v26, 8, v25
	v_bitop3_b32 v16, v23, v16, v17 bitop3:0xde
	v_or_b32_e32 v19, v19, v22
	v_lshrrev_b32_e32 v25, 1, v25
	v_lshlrev_b32_e32 v24, 6, v24
	v_and_b32_e32 v27, 48, v23
	v_add_u32_e32 v190, 0, v16
	v_lshlrev_b32_e32 v16, 9, v19
	v_or_b32_e32 v19, v25, v22
	v_or3_b32 v16, v16, v24, v27
	v_lshlrev_b32_e32 v19, 9, v19
	v_lshlrev_b32_e32 v53, 4, v52
	v_lshlrev_b32_e32 v18, 8, v18
	v_or3_b32 v19, v19, v24, v27
	v_add_u32_e32 v191, 0, v16
	v_add_u32_e32 v202, 0, v19
	s_waitcnt vmcnt(0)
	v_and_b32_e32 v181, 63, v52
	s_add_i32 s22, 0, 0x11800
	s_mov_b64 s[26:27], 0x4000
	s_mov_b32 s41, s40
	v_lshl_add_u64 v[62:63], v[50:51], 0, s[26:27]
	s_mov_b64 s[26:27], 0x6000
	s_mov_b32 s42, s40
	s_mov_b32 s43, s40
	s_waitcnt vmcnt(11)
	ds_write_b128 v191, v[0:3]
	s_waitcnt vmcnt(10)
	ds_write_b128 v202, v[4:7]
	s_waitcnt vmcnt(9)
	ds_write_b128 v190, v[8:11] offset:32768
	v_bitop3_b32 v0, v23, v18, v17 bitop3:0xde
	v_lshlrev_b32_e32 v8, 8, v183
	v_and_b32_e32 v9, 0x70, v53
	v_add_u32_e32 v203, 0, v0
	v_bitop3_b32 v0, v192, v8, v9 bitop3:0xde
	v_add_u32_e32 v204, 0, v0
	s_waitcnt vmcnt(8)
	ds_write_b128 v203, v[12:15] offset:32768
	s_waitcnt lgkmcnt(0)
	s_barrier
	ds_read_b128 v[0:3], v204 offset:32768
	ds_read_b128 v[4:7], v204 offset:40960
	s_waitcnt vmcnt(7) lgkmcnt(1)
	v_mfma_f32_32x32x16_bf16 v[32:47], v[0:3], v[116:119], 0
	v_or_b32_e32 v0, 32, v192
	v_bitop3_b32 v0, v0, v8, v9 bitop3:0xde
	v_add_u32_e32 v211, 0, v0
	v_lshlrev_b32_e32 v10, 3, v181
	v_lshlrev_b32_e32 v12, 1, v52
	s_mov_b32 s44, s40
	s_mov_b32 s45, s40
	s_waitcnt lgkmcnt(0)
	v_mfma_f32_32x32x16_bf16 v[16:31], v[4:7], v[116:119], 0
	ds_read_b128 v[0:3], v211 offset:32768
	ds_read_b128 v[4:7], v211 offset:40960
	s_mov_b32 s46, s40
	s_mov_b32 s47, s40
	s_mov_b32 s48, s40
	s_mov_b32 s49, s40
	s_mov_b32 s50, s40
	s_mov_b32 s51, s40
	s_waitcnt vmcnt(6) lgkmcnt(1)
	v_mfma_f32_32x32x16_bf16 v[32:47], v[0:3], v[112:115], v[32:47]
	v_or_b32_e32 v0, 64, v192
	v_bitop3_b32 v0, v0, v8, v9 bitop3:0xde
	v_add_u32_e32 v210, 0, v0
	s_mov_b32 s52, s40
	s_mov_b32 s53, s40
	s_mov_b32 s54, s40
	s_mov_b32 s55, s40
	s_waitcnt lgkmcnt(0)
	v_mfma_f32_32x32x16_bf16 v[16:31], v[4:7], v[112:115], v[16:31]
	ds_read_b128 v[0:3], v210 offset:32768
	ds_read_b128 v[4:7], v210 offset:40960
	v_lshl_add_u64 v[64:65], v[50:51], 0, s[26:27]
	v_lshl_add_u64 v[58:59], s[2:3], 0, v[64:65]
	v_lshl_add_u64 v[66:67], s[0:1], 0, v[64:65]
	s_mov_b64 s[26:27], 0xa000
	s_cmp_lg_u32 0, -1
	s_mov_b32 s20, 1
	s_waitcnt vmcnt(5) lgkmcnt(1)
	v_mfma_f32_32x32x16_bf16 v[32:47], v[0:3], v[124:127], v[32:47]
	v_or_b32_e32 v0, 0x60, v192
	v_bitop3_b32 v0, v0, v8, v9 bitop3:0xde
	v_add_u32_e32 v208, 0, v0
	v_cmp_gt_u32_e64 s[36:37], 32, v181
	v_mov_b32_e32 v187, 0
	s_waitcnt lgkmcnt(0)
	v_mfma_f32_32x32x16_bf16 v[16:31], v[4:7], v[124:127], v[16:31]
	ds_read_b128 v[0:3], v208 offset:32768
	ds_read_b128 v[4:7], v208 offset:40960
	s_waitcnt vmcnt(4) lgkmcnt(1)
	v_mfma_f32_32x32x16_bf16 v[32:47], v[0:3], v[120:123], v[32:47]
	v_or_b32_e32 v0, 0x80, v192
	v_bitop3_b32 v0, v0, v8, v9 bitop3:0xde
	v_add_u32_e32 v206, 0, v0
	s_waitcnt lgkmcnt(0)
; #define SLOAD(i, k0) do { sr_[i].vs0 = *(const bf16x8*)(&Vh[(long)((k0) + sr) * LDK + sc]); sr_[i].vs1 = *(const bf16x8*)(&Vh[(long)((k0) + 32 + sr) * LDK + sc]); \
;     sr_[i].ks0 = *(const bf16x8*)(&Kh[(long)((k0) + sr) * LDK + sc]); sr_[i].ks1 = *(const bf16x8*)(&Kh[(long)((k0) + 32 + sr) * LDK + sc]); } while (0)
; __device__ __forceinline__ void partialSM(f32x16& p0, f32x16& p1, float& m_reg, float& mn, float& alpha) {
;   constexpr float C = SCALE * 1.4426950408889634f;
;   float pmax = p0[0];
; #pragma unroll
;   for (int r = 1; r < 16; ++r) pmax = fmaxf(pmax, p0[r]);
; #pragma unroll
;   for (int r = 0; r < 16; ++r) pmax = fmaxf(pmax, p1[r]);
;   { auto rr = __builtin_amdgcn_permlane32_swap(__float_as_uint(pmax), __float_as_uint(pmax), false, false);
;     pmax = fmaxf(__uint_as_float(rr[0]), __uint_as_float(rr[1])); }
;   if (__builtin_expect(__all(pmax - m_reg <= THR / SCALE), 1)) { mn = m_reg; alpha = 1.f; }
;   else { mn = fmaxf(m_reg, pmax); alpha = __builtin_amdgcn_exp2f((m_reg - mn) * C); m_reg = mn; }
;   float mnC = -mn * C;
; #pragma unroll
;   for (int r = 0; r < 16; ++r) p0[r] = fmaf(p0[r], C, mnC);
; #pragma unroll
;   for (int r = 0; r < 16; ++r) p1[r] = fmaf(p1[r], C, mnC);
; template <int MODE, int SDEPTH, bool SIMPLE>
; __device__ __forceinline__ void attn_body(const Unit& U, char* lds, const int tid) {
;     ...
;   qkt(pA0, pA1, K_lds, qr, r32, hi); amask<MODE>(pA0, pA1, 0, U, wid, r32, hi, tbl); partialSM(pA0, pA1, m_reg, mnA, alA);
;   SLOAD(SO, KVBLK); if constexpr (SDEPTH == 2) { if (2 < NT) SLOAD(SE, 2 * KVBLK); }
	v_mfma_f32_32x32x16_bf16 v[16:31], v[4:7], v[120:123], v[16:31]
	ds_read_b128 v[0:3], v206 offset:32768
	ds_read_b128 v[4:7], v206 offset:40960
	s_waitcnt vmcnt(3) lgkmcnt(1)
	v_mfma_f32_32x32x16_bf16 v[32:47], v[0:3], v[108:111], v[32:47]
	v_or_b32_e32 v0, 0xa0, v192
	v_bitop3_b32 v0, v0, v8, v9 bitop3:0xde
	v_add_u32_e32 v205, 0, v0
	ds_read_b128 v[0:3], v205 offset:32768
	s_waitcnt lgkmcnt(1)
	v_mfma_f32_32x32x16_bf16 v[16:31], v[4:7], v[108:111], v[16:31]
	v_and_b32_e32 v4, 0x3fffffc0, v52
	v_lshl_add_u32 v185, v4, 2, s22
	ds_read_b128 v[4:7], v205 offset:40960
	s_cselect_b32 s22, 0, 0
	v_lshl_add_u32 v186, v183, 2, v185
	s_waitcnt vmcnt(2) lgkmcnt(1)
	v_mfma_f32_32x32x16_bf16 v[32:47], v[0:3], v[104:107], v[32:47]
	v_and_b32_e32 v0, 0xc0, v53
	v_and_or_b32 v11, v10, 24, v0
	v_or_b32_e32 v0, 0xc0, v192
	v_bitop3_b32 v0, v0, v8, v9 bitop3:0xde
	v_add_u32_e32 v207, 0, v0
	ds_read_b128 v[0:3], v207 offset:32768
	s_waitcnt lgkmcnt(1)
	v_mfma_f32_32x32x16_bf16 v[16:31], v[4:7], v[104:107], v[16:31]
	v_and_b32_e32 v4, 32, v12
	v_and_b32_e32 v5, 0x100, v10
	v_or3_b32 v53, v11, v4, v5
	ds_read_b128 v[4:7], v207 offset:40960
	v_add_u32_e32 v189, s22, v53
	s_waitcnt vmcnt(1) lgkmcnt(1)
	v_mfma_f32_32x32x16_bf16 v[32:47], v[0:3], v[100:103], v[32:47]
	v_or_b32_e32 v0, 0xe0, v192
	v_bitop3_b32 v0, v0, v8, v9 bitop3:0xde
	v_add_u32_e32 v209, 0, v0
	ds_read_b128 v[0:3], v209 offset:32768
	ds_read_b128 v[54:57], v209 offset:40960
	s_waitcnt lgkmcnt(2)
	v_mfma_f32_32x32x16_bf16 v[16:31], v[4:7], v[100:103], v[16:31]
	s_waitcnt vmcnt(0) lgkmcnt(1)
	v_mfma_f32_32x32x16_bf16 v[32:47], v[0:3], v[96:99], v[32:47]
	v_mov_b64_e32 v[0:1], s[40:41]
	v_mov_b64_e32 v[2:3], s[42:43]
	v_mov_b64_e32 v[4:5], s[44:45]
	v_mov_b64_e32 v[6:7], s[46:47]
	v_mov_b64_e32 v[8:9], s[48:49]
	v_mov_b64_e32 v[10:11], s[50:51]
	v_mov_b64_e32 v[12:13], s[52:53]
	s_waitcnt lgkmcnt(0)
	v_mfma_f32_32x32x16_bf16 v[16:31], v[54:57], v[96:99], v[16:31]
	s_nop 2
	v_max_f32_e32 v54, v33, v33
	v_max_f32_e32 v55, v32, v32
	v_max_f32_e32 v54, v55, v54
	v_max3_f32 v54, v54, v34, v35
	v_max3_f32 v54, v54, v36, v37
	v_max3_f32 v54, v54, v38, v39
	v_max3_f32 v54, v54, v40, v41
	v_max3_f32 v54, v54, v42, v43
	v_max3_f32 v54, v54, v44, v45
	v_max3_f32 v54, v54, v46, v47
	v_max3_f32 v70, v54, v16, v17
	v_max3_f32 v70, v70, v18, v19
	v_max3_f32 v70, v70, v20, v21
	v_max3_f32 v70, v70, v22, v23
	v_max3_f32 v70, v70, v24, v25
	v_max3_f32 v70, v70, v26, v27
	v_mov_b64_e32 v[14:15], s[54:55]
	v_lshl_add_u64 v[54:55], s[2:3], 0, v[62:63]
	v_lshl_add_u64 v[62:63], s[0:1], 0, v[62:63]
	v_max3_f32 v70, v70, v28, v29
	s_mov_b64 s[44:45], 0x8000
	global_load_dwordx4 v[54:57], v[54:55], off
	s_nop 0
	global_load_dwordx4 v[58:61], v[58:59], off
	s_nop 0
	global_load_dwordx4 v[62:65], v[62:63], off
	s_nop 0
	global_load_dwordx4 v[66:69], v[66:67], off
	v_max3_f32 v76, v70, v30, v31
	v_lshl_add_u64 v[70:71], v[50:51], 0, s[44:45]
	v_lshl_add_u64 v[72:73], s[2:3], 0, v[70:71]
	v_lshl_add_u64 v[50:51], v[50:51], 0, s[26:27]
	v_lshl_add_u64 v[70:71], s[0:1], 0, v[70:71]
	v_lshl_add_u64 v[74:75], s[2:3], 0, v[50:51]
	global_load_dwordx4 v[128:131], v[72:73], off
	global_load_dwordx4 v[136:139], v[74:75], off
	v_lshl_add_u64 v[50:51], s[0:1], 0, v[50:51]
	global_load_dwordx4 v[132:135], v[70:71], off
	global_load_dwordx4 v[140:143], v[50:51], off
	v_mov_b32_e32 v77, v76
	s_nop 1
	v_permlane32_swap_b32_e32 v76, v77
	v_max_f32_e32 v50, v77, v77
	v_max_f32_e32 v51, v76, v76
	v_max_f32_e32 v50, v51, v50
	v_add_f32_e32 v51, 0x7149f2ca, v50
	v_max_f32_e32 v50, 0xf149f2ca, v50
	v_cmp_ge_f32_e32 vcc, s18, v51
	v_sub_f32_e32 v51, 0xf149f2ca, v50
	v_mul_f32_e32 v51, 0x3e0293ee, v51
	v_exp_f32_e32 v51, v51
	s_cmp_eq_u64 vcc, exec
	s_cselect_b64 vcc, -1, 0
	v_cndmask_b32_e32 v164, v50, v228, vcc
	v_mul_f32_e32 v50, 0xbe0293ee, v164
	s_or_b32 s0, s15, s21
	v_cndmask_b32_e64 v212, v51, 1.0, vcc
	v_mov_b32_e32 v51, v50
	s_ashr_i32 s1, s0, 31
	v_fmamk_f32 v32, v32, 0x3e0293ee, v50
	v_fmamk_f32 v33, v33, 0x3e0293ee, v50
	v_fmamk_f32 v34, v34, 0x3e0293ee, v50
	v_fmamk_f32 v35, v35, 0x3e0293ee, v50
	v_fmamk_f32 v36, v36, 0x3e0293ee, v50
	v_fmamk_f32 v37, v37, 0x3e0293ee, v50
	v_fmamk_f32 v38, v38, 0x3e0293ee, v50
	v_fmamk_f32 v39, v39, 0x3e0293ee, v50
	v_fmamk_f32 v40, v40, 0x3e0293ee, v50
	v_fmamk_f32 v41, v41, 0x3e0293ee, v50
	v_fmamk_f32 v42, v42, 0x3e0293ee, v50
	v_fmamk_f32 v43, v43, 0x3e0293ee, v50
	v_fmamk_f32 v44, v44, 0x3e0293ee, v50
	v_fmamk_f32 v45, v45, 0x3e0293ee, v50
	v_fmamk_f32 v46, v46, 0x3e0293ee, v50
	v_fmac_f32_e32 v51, 0x3e0293ee, v47
	s_lshl_b64 s[0:1], s[0:1], 21
	v_pk_fma_f32 v[154:155], v[18:19], s[12:13], v[50:51] op_sel_hi:[1,0,0]
	v_pk_fma_f32 v[156:157], v[16:17], s[12:13], v[50:51] op_sel_hi:[1,0,0]
	v_exp_f32_e32 v161, v32
	v_exp_f32_e32 v162, v33
	v_exp_f32_e32 v174, v34
	v_exp_f32_e32 v175, v35
	v_exp_f32_e32 v216, v36
	v_exp_f32_e32 v219, v37
	v_exp_f32_e32 v163, v38
	v_exp_f32_e32 v173, v39
	v_exp_f32_e32 v168, v40
	v_exp_f32_e32 v170, v41
	v_exp_f32_e32 v171, v42
	v_exp_f32_e32 v172, v43
	v_exp_f32_e32 v165, v44
	v_exp_f32_e32 v166, v45
	v_exp_f32_e32 v167, v46
	v_exp_f32_e32 v169, v51
	v_lshl_add_u64 v[16:17], s[0:1], 0, v[48:49]
	v_and_b32_e32 v18, 15, v52
	s_waitcnt vmcnt(4)
	s_addk_i32 s22, 0x4000
	v_lshl_or_b32 v16, v18, 4, v16
	v_pk_fma_f32 v[150:151], v[30:31], s[12:13], v[50:51] op_sel_hi:[1,0,0]
	v_pk_fma_f32 v[152:153], v[28:29], s[12:13], v[50:51] op_sel_hi:[1,0,0]
	v_pk_fma_f32 v[158:159], v[26:27], s[12:13], v[50:51] op_sel_hi:[1,0,0]
	v_pk_fma_f32 v[144:145], v[24:25], s[12:13], v[50:51] op_sel_hi:[1,0,0]
	v_pk_fma_f32 v[146:147], v[22:23], s[12:13], v[50:51] op_sel_hi:[1,0,0]
	v_pk_fma_f32 v[148:149], v[20:21], s[12:13], v[50:51] op_sel_hi:[1,0,0]
	s_waitcnt vmcnt(7)
; #define SBAR() __builtin_amdgcn_sched_barrier(0)
; #define SWRITE(b, i) do { *(bf16x8*)(V_lds + (b) * SHM_V + vst0) = sr_[i].vs0;          \
;     *(bf16x8*)(V_lds + (b) * SHM_V + vst1) = sr_[i].vs1; int kc = sc * 2;               \
;     *(bf16x8*)(K_lds + (b) * SHM_K + KSWZ(sr, kc)) = sr_[i].ks0;                       \
;     *(bf16x8*)(K_lds + (b) * SHM_K + KSWZ(32 + sr, kc)) = sr_[i].ks1; } while (0)
; #define SWAIT() do { if constexpr (SDEPTH == 2) asm volatile("s_waitcnt vmcnt(4)" ::: "memory"); else asm volatile("s_waitcnt vmcnt(0)" ::: "memory"); } while (0)
; __device__ __forceinline__ void finishSM(f32x16& p0, f32x16& p1, float alpha, float& l_reg, bf16x8& pa0, bf16x8& pa1, bf16x8& pa2, bf16x8& pa3) {
;     ...
;   for (int r = 0; r < 16; ++r) p1[r] = __builtin_amdgcn_exp2f(p1[r]);
;   float ps = 0;
; #pragma unroll
;   for (int r = 0; r < 16; ++r) ps += p0[r];
; #pragma unroll
;   for (int r = 0; r < 16; ++r) ps += p1[r];
; __device__ __forceinline__ void qkt(f32x16& p0, f32x16& p1, const char* Ks, const bf16x8* qr, int r32, int hi) {
;   p0 = f32x16{}; p1 = f32x16{};
; #pragma unroll
;   for (int d0 = 0; d0 < 8; ++d0) { int cb = (d0 * 16 + hi * 8) * 2;
;     bf16x8 b0 = *reinterpret_cast<const bf16x8*>(Ks + KSWZ(r32, cb));
;     bf16x8 b1 = *reinterpret_cast<const bf16x8*>(Ks + KSWZ(32 + r32, cb));
;     p0 = __builtin_amdgcn_mfma_f32_32x32x16_bf16(b0, qr[d0], p0, 0, 0, 0);
;     p1 = __builtin_amdgcn_mfma_f32_32x32x16_bf16(b1, qr[d0], p1, 0, 0, 0); }
; template <int MODE, int SDEPTH, bool SIMPLE>
; __device__ __forceinline__ void attn_body(const Unit& U, char* lds, const int tid) {
;     ...
;   SWAIT(); SWRITE(1, SO); __syncthreads();
;   for (int j = 1; j + 1 < NT; j += 2) {
;     SBAR(); qkt(pB0, pB1, K_lds + SHM_K, qr, r32, hi); amask<MODE>(pB0, pB1, j, U, wid, r32, hi, tbl);
;     finishSM(pA0, pA1, alA, l_reg, pa0, pa1, pa2, pa3); SBAR();
	ds_write_b128 v191, v[54:57] offset:16384
	s_waitcnt vmcnt(6)
	ds_write_b128 v202, v[58:61] offset:16384
	s_waitcnt vmcnt(5)
	ds_write_b128 v190, v[62:65] offset:49152
	s_waitcnt vmcnt(4)
	ds_write_b128 v203, v[66:69] offset:49152
	v_add_u32_e32 v188, s22, v53
	v_lshl_add_u64 v[178:179], s[10:11], 0, v[16:17]
	s_nop 0
	v_readfirstlane_b32 s66, v178
	v_readfirstlane_b32 s67, v179
	s_nop 1
	v_subrev_u32_e32 v178, s66, v178
	s_sub_u32 s6, s66, 0x6000
	s_subb_u32 s7, s67, 0
	s_sub_u32 s4, s6, 0x800000
	s_subb_u32 s5, s7, 0
	v_add_u32_e32 v179, 0x2000, v178
	v_mov_b64_e32 v[62:63], v[14:15]
	v_mov_b64_e32 v[46:47], v[14:15]
	v_mov_b64_e32 v[30:31], v[14:15]
	v_mov_b64_e32 v[60:61], v[12:13]
	v_mov_b64_e32 v[58:59], v[10:11]
	v_mov_b64_e32 v[56:57], v[8:9]
	v_mov_b64_e32 v[54:55], v[6:7]
	v_mov_b64_e32 v[52:53], v[4:5]
	v_mov_b64_e32 v[50:51], v[2:3]
	v_mov_b64_e32 v[48:49], v[0:1]
	v_mov_b64_e32 v[44:45], v[12:13]
	v_mov_b64_e32 v[42:43], v[10:11]
	v_mov_b64_e32 v[40:41], v[8:9]
	v_mov_b64_e32 v[38:39], v[6:7]
	v_mov_b64_e32 v[36:37], v[4:5]
	v_mov_b64_e32 v[34:35], v[2:3]
	v_mov_b64_e32 v[32:33], v[0:1]
	v_mov_b64_e32 v[28:29], v[12:13]
	v_mov_b64_e32 v[26:27], v[10:11]
	v_mov_b64_e32 v[24:25], v[8:9]
	v_mov_b64_e32 v[22:23], v[6:7]
	v_mov_b64_e32 v[20:21], v[4:5]
	v_mov_b64_e32 v[18:19], v[2:3]
	v_mov_b64_e32 v[16:17], v[0:1]
	s_waitcnt lgkmcnt(0)
	s_barrier
	.p2align	6
.LBB0_199:
	ds_read_b128 v[64:67], v204 offset:49152
	ds_read_b128 v[68:71], v204 offset:57344
	ds_read_b128 v[220:223], v211 offset:49152
	ds_read_b128 v[234:237], v211 offset:57344
	v_add_f32_e32 v160, v162, v161
	s_waitcnt lgkmcnt(3)
	v_mfma_f32_32x32x16_bf16 v[80:95], v[64:67], v[116:119], 0
	v_add_f32_e32 v160, v174, v160
	v_add_f32_e32 v160, v175, v160
	v_add_f32_e32 v160, v216, v160
	v_add_f32_e32 v160, v219, v160
	v_add_f32_e32 v160, v163, v160
	v_add_f32_e32 v160, v173, v160
	v_add_f32_e32 v160, v168, v160
	s_waitcnt lgkmcnt(2)
	v_mfma_f32_32x32x16_bf16 v[64:79], v[68:71], v[116:119], 0
	v_add_f32_e32 v160, v170, v160
	v_add_f32_e32 v160, v171, v160
	v_add_f32_e32 v160, v172, v160
	v_exp_f32_e32 v156, v156
	v_add_f32_e32 v160, v165, v160
	v_exp_f32_e32 v157, v157
	v_add_f32_e32 v160, v166, v160
	s_waitcnt lgkmcnt(1)
	v_mfma_f32_32x32x16_bf16 v[80:95], v[220:223], v[112:115], v[80:95]
	v_exp_f32_e32 v154, v154
	v_add_f32_e32 v160, v167, v160
	v_exp_f32_e32 v155, v155
	v_add_f32_e32 v160, v169, v160
	v_exp_f32_e32 v148, v148
	v_add_f32_e32 v160, v156, v160
	v_exp_f32_e32 v149, v149
	s_waitcnt lgkmcnt(0)
	v_mfma_f32_32x32x16_bf16 v[64:79], v[234:237], v[112:115], v[64:79]
	ds_read_b128 v[220:223], v210 offset:49152
	ds_read_b128 v[234:237], v210 offset:57344
	v_add_f32_e32 v160, v157, v160
	v_exp_f32_e32 v146, v146
	v_add_f32_e32 v160, v154, v160
	v_exp_f32_e32 v147, v147
	v_add_f32_e32 v160, v155, v160
	v_exp_f32_e32 v144, v144
	s_waitcnt lgkmcnt(1)
	v_mfma_f32_32x32x16_bf16 v[80:95], v[220:223], v[124:127], v[80:95]
	v_add_f32_e32 v160, v148, v160
	v_exp_f32_e32 v145, v145
	v_add_f32_e32 v160, v149, v160
	v_exp_f32_e32 v158, v158
	v_add_f32_e32 v160, v146, v160
	v_exp_f32_e32 v159, v159
	v_add_f32_e32 v160, v147, v160
	s_waitcnt lgkmcnt(0)
	v_mfma_f32_32x32x16_bf16 v[64:79], v[234:237], v[124:127], v[64:79]
	ds_read_b128 v[220:223], v208 offset:49152
	ds_read_b128 v[234:237], v208 offset:57344
	v_exp_f32_e32 v152, v152
	v_add_f32_e32 v160, v144, v160
	v_exp_f32_e32 v153, v153
	v_add_f32_e32 v160, v145, v160
	v_exp_f32_e32 v150, v150
	v_add_f32_e32 v160, v158, v160
	s_waitcnt lgkmcnt(1)
	v_mfma_f32_32x32x16_bf16 v[80:95], v[220:223], v[120:123], v[80:95]
	v_exp_f32_e32 v151, v151
	v_add_f32_e32 v160, v159, v160
	v_add_f32_e32 v160, v152, v160
	v_add_f32_e32 v160, v153, v160
	v_add_f32_e32 v160, v150, v160
	v_add_f32_e32 v213, v151, v160
	v_mov_b32_e32 v214, v213
	s_waitcnt lgkmcnt(0)
	v_mfma_f32_32x32x16_bf16 v[64:79], v[234:237], v[120:123], v[64:79]
	ds_read_b128 v[220:223], v206 offset:49152
	ds_read_b128 v[234:237], v206 offset:57344
	v_cvt_pk_bf16_f32 v160, v161, v162
	v_cvt_pk_bf16_f32 v162, v216, v219
	v_permlane32_swap_b32_e32 v213, v214
	v_cvt_pk_bf16_f32 v161, v174, v175
	v_cvt_pk_bf16_f32 v163, v163, v173
	s_waitcnt lgkmcnt(1)
	v_mfma_f32_32x32x16_bf16 v[80:95], v[220:223], v[108:111], v[80:95]
	v_permlane32_swap_b32_e32 v160, v162
	v_cvt_pk_bf16_f32 v170, v168, v170
	v_cvt_pk_bf16_f32 v171, v171, v172
	v_cvt_pk_bf16_f32 v172, v165, v166
	v_cvt_pk_bf16_f32 v173, v167, v169
	v_cvt_pk_bf16_f32 v166, v156, v157
	s_waitcnt lgkmcnt(0)
	v_mfma_f32_32x32x16_bf16 v[64:79], v[234:237], v[108:111], v[64:79]
	ds_read_b128 v[220:223], v205 offset:49152
	ds_read_b128 v[234:237], v205 offset:57344
	v_cvt_pk_bf16_f32 v167, v154, v155
	v_cvt_pk_bf16_f32 v168, v148, v149
	v_cvt_pk_bf16_f32 v169, v146, v147
	v_cvt_pk_bf16_f32 v216, v144, v145
	v_cvt_pk_bf16_f32 v217, v158, v159
	v_cvt_pk_bf16_f32 v218, v152, v153
	s_waitcnt lgkmcnt(1)
	v_mfma_f32_32x32x16_bf16 v[80:95], v[220:223], v[104:107], v[80:95]
	v_cvt_pk_bf16_f32 v219, v150, v151
	v_permlane32_swap_b32_e32 v161, v163
	v_permlane32_swap_b32_e32 v170, v172
	v_permlane32_swap_b32_e32 v171, v173
	s_waitcnt lgkmcnt(0)
	v_mfma_f32_32x32x16_bf16 v[64:79], v[234:237], v[104:107], v[64:79]
	ds_read_b64_tr_b16 v[144:145], v189 offset:0
	ds_read_b64_tr_b16 v[146:147], v189 offset:0x800
	ds_read_b64_tr_b16 v[148:149], v189 offset:0x1000
	ds_read_b64_tr_b16 v[150:151], v189 offset:0x1800
	ds_read_b64_tr_b16 v[152:153], v189 offset:0x2000
	ds_read_b64_tr_b16 v[154:155], v189 offset:0x2800
	ds_read_b64_tr_b16 v[156:157], v189 offset:0x3000
	ds_read_b64_tr_b16 v[158:159], v189 offset:0x3800
	ds_read_b128 v[220:223], v207 offset:49152
	ds_read_b128 v[234:237], v207 offset:57344
	v_permlane32_swap_b32_e32 v166, v168
	v_permlane32_swap_b32_e32 v167, v169
	v_permlane32_swap_b32_e32 v216, v218
	s_waitcnt lgkmcnt(1)
; #define SBAR() __builtin_amdgcn_sched_barrier(0)
; __device__ __forceinline__ void partialSM(f32x16& p0, f32x16& p1, float& m_reg, float& mn, float& alpha) {
;   constexpr float C = SCALE * 1.4426950408889634f;
;   float pmax = p0[0];
; #pragma unroll
;   for (int r = 1; r < 16; ++r) pmax = fmaxf(pmax, p0[r]);
; #pragma unroll
;   for (int r = 0; r < 16; ++r) pmax = fmaxf(pmax, p1[r]);
;   { auto rr = __builtin_amdgcn_permlane32_swap(__float_as_uint(pmax), __float_as_uint(pmax), false, false);
;     pmax = fmaxf(__uint_as_float(rr[0]), __uint_as_float(rr[1])); }
;   if (__builtin_expect(__all(pmax - m_reg <= THR / SCALE), 1)) { mn = m_reg; alpha = 1.f; }
;   else { mn = fmaxf(m_reg, pmax); alpha = __builtin_amdgcn_exp2f((m_reg - mn) * C); m_reg = mn; }
; template <int D0> __device__ __forceinline__ void pv_one(f32x16& od, int vb, bf16x8 pa0, bf16x8 pa1, bf16x8 pa2, bf16x8 pa3) {
;   const s16x4 l0 = tr_read<v_rd_off(D0, 0, 0)>(vb), h0 = tr_read<v_rd_off(D0, 0, 1)>(vb), l1 = tr_read<v_rd_off(D0, 1, 0)>(vb), h1 = tr_read<v_rd_off(D0, 1, 1)>(vb);
;   const s16x4 l2 = tr_read<v_rd_off(D0, 2, 0)>(vb), h2 = tr_read<v_rd_off(D0, 2, 1)>(vb), l3 = tr_read<v_rd_off(D0, 3, 0)>(vb), h3 = tr_read<v_rd_off(D0, 3, 1)>(vb);
;   asm volatile("s_waitcnt lgkmcnt(0)" ::: "memory"); SBAR();
;     ...
;   od = __builtin_amdgcn_mfma_f32_32x32x16_bf16(pa0, PK(l0, h0), od, 0, 0, 0);
;   od = __builtin_amdgcn_mfma_f32_32x32x16_bf16(pa1, PK(l1, h1), od, 0, 0, 0);
;   od = __builtin_amdgcn_mfma_f32_32x32x16_bf16(pa2, PK(l2, h2), od, 0, 0, 0);
;   od = __builtin_amdgcn_mfma_f32_32x32x16_bf16(pa3, PK(l3, h3), od, 0, 0, 0);
;     ...
; }
; __device__ __forceinline__ void pv_d0(f32x16* o, int vb, bf16x8 pa0, bf16x8 pa1, bf16x8 pa2, bf16x8 pa3) {
;   pv_one<0>(o[0], vb, pa0, pa1, pa2, pa3); pv_one<1>(o[1], vb, pa0, pa1, pa2, pa3); pv_one<2>(o[2], vb, pa0, pa1, pa2, pa3); pv_one<3>(o[3], vb, pa0, pa1, pa2, pa3);
	v_mfma_f32_32x32x16_bf16 v[80:95], v[220:223], v[100:103], v[80:95]
	v_permlane32_swap_b32_e32 v217, v219
	s_waitcnt lgkmcnt(0)
	v_mfma_f32_32x32x16_bf16 v[64:79], v[234:237], v[100:103], v[64:79]
	ds_read_b128 v[220:223], v209 offset:49152
	ds_read_b128 v[234:237], v209 offset:57344
	s_waitcnt lgkmcnt(1)
	v_mfma_f32_32x32x16_bf16 v[80:95], v[220:223], v[96:99], v[80:95]
	s_waitcnt lgkmcnt(0)
	v_mfma_f32_32x32x16_bf16 v[64:79], v[234:237], v[96:99], v[64:79]
	s_waitcnt lgkmcnt(0)
	s_nop 0
	v_mfma_f32_32x32x16_bf16 v[0:15], v[160:163], v[144:147], v[0:15]
	ds_read_b64_tr_b16 v[220:221], v189 offset:0x200
	ds_read_b64_tr_b16 v[222:223], v189 offset:0xa00
	v_mfma_f32_32x32x16_bf16 v[0:15], v[170:173], v[148:151], v[0:15]
	ds_read_b64_tr_b16 v[234:235], v189 offset:0x1200
	ds_read_b64_tr_b16 v[236:237], v189 offset:0x1a00
	v_mfma_f32_32x32x16_bf16 v[0:15], v[166:169], v[152:155], v[0:15]
	ds_read_b64_tr_b16 v[238:239], v189 offset:0x2200
	ds_read_b64_tr_b16 v[240:241], v189 offset:0x2a00
	v_mfma_f32_32x32x16_bf16 v[0:15], v[216:219], v[156:159], v[0:15]
	ds_read_b64_tr_b16 v[242:243], v189 offset:0x3200
	ds_read_b64_tr_b16 v[244:245], v189 offset:0x3a00
	global_load_dwordx4 v[144:147], v178, s[6:7]
	global_load_dwordx4 v[148:151], v179, s[6:7]
	global_load_dwordx4 v[152:155], v178, s[4:5]
	global_load_dwordx4 v[156:159], v179, s[4:5]
	s_add_u32 s6, s6, 0x4000
	s_addc_u32 s7, s7, 0
	s_add_u32 s4, s4, 0x4000
	s_addc_u32 s5, s5, 0
	s_waitcnt lgkmcnt(0)
	v_mfma_f32_32x32x16_bf16 v[48:63], v[160:163], v[220:223], v[48:63]
	ds_read_b64_tr_b16 v[220:221], v189 offset:0x400
	ds_read_b64_tr_b16 v[222:223], v189 offset:0xc00
	v_mfma_f32_32x32x16_bf16 v[48:63], v[170:173], v[234:237], v[48:63]
	ds_read_b64_tr_b16 v[234:235], v189 offset:0x1400
	ds_read_b64_tr_b16 v[236:237], v189 offset:0x1c00
	v_mfma_f32_32x32x16_bf16 v[48:63], v[166:169], v[238:241], v[48:63]
	ds_read_b64_tr_b16 v[238:239], v189 offset:0x2400
	ds_read_b64_tr_b16 v[240:241], v189 offset:0x2c00
	v_mfma_f32_32x32x16_bf16 v[48:63], v[216:219], v[242:245], v[48:63]
	ds_read_b64_tr_b16 v[242:243], v189 offset:0x3400
	ds_read_b64_tr_b16 v[244:245], v189 offset:0x3c00
	s_waitcnt lgkmcnt(0)
	v_mfma_f32_32x32x16_bf16 v[32:47], v[160:163], v[220:223], v[32:47]
	ds_read_b64_tr_b16 v[220:221], v189 offset:0x600
	ds_read_b64_tr_b16 v[222:223], v189 offset:0xe00
	v_mfma_f32_32x32x16_bf16 v[32:47], v[170:173], v[234:237], v[32:47]
	ds_read_b64_tr_b16 v[234:235], v189 offset:0x1600
	ds_read_b64_tr_b16 v[236:237], v189 offset:0x1e00
	v_mfma_f32_32x32x16_bf16 v[32:47], v[166:169], v[238:241], v[32:47]
	ds_read_b64_tr_b16 v[238:239], v189 offset:0x2600
	ds_read_b64_tr_b16 v[240:241], v189 offset:0x2e00
	v_mfma_f32_32x32x16_bf16 v[32:47], v[216:219], v[242:245], v[32:47]
	ds_read_b64_tr_b16 v[242:243], v189 offset:0x3600
	ds_read_b64_tr_b16 v[244:245], v189 offset:0x3e00
	s_waitcnt lgkmcnt(0)
	v_mfma_f32_32x32x16_bf16 v[16:31], v[160:163], v[220:223], v[16:31]
	v_max_f32_e32 v160, v80, v81
	v_max3_f32 v160, v160, v82, v83
	v_max3_f32 v160, v160, v84, v85
	v_max3_f32 v160, v160, v86, v87
	v_max3_f32 v160, v160, v88, v89
	v_max3_f32 v160, v160, v90, v91
	v_max3_f32 v160, v160, v92, v93
	v_mfma_f32_32x32x16_bf16 v[16:31], v[170:173], v[234:237], v[16:31]
	v_max3_f32 v160, v160, v94, v95
	v_max3_f32 v160, v160, v64, v65
	v_max3_f32 v160, v160, v66, v67
	v_max3_f32 v160, v160, v68, v69
	v_max3_f32 v160, v160, v70, v71
	v_max3_f32 v160, v160, v72, v73
	v_max3_f32 v160, v160, v74, v75
	v_max3_f32 v160, v160, v76, v77
	v_mfma_f32_32x32x16_bf16 v[16:31], v[166:169], v[238:241], v[16:31]
	v_max3_f32 v160, v160, v78, v79
	v_mov_b32_e32 v161, v160
	s_nop 1
	v_permlane32_swap_b32_e32 v160, v161
	v_max_f32_e32 v160, v160, v161
	v_sub_f32_e32 v161, v160, v164
	v_cmp_ge_f32_e32 vcc, s18, v161
	v_max_f32_e32 v160, v164, v160
	v_mfma_f32_32x32x16_bf16 v[16:31], v[216:219], v[242:245], v[16:31]
	v_sub_f32_e32 v161, v164, v160
	v_mul_f32_e32 v161, 0x3e0293ee, v161
	v_exp_f32_e32 v161, v161
	s_cmp_eq_u64 vcc, exec
	s_cselect_b64 s[0:1], -1, 0
	s_barrier
	s_waitcnt vmcnt(4)
	v_cndmask_b32_e64 v215, v161, 1.0, s[0:1]
	v_cmp_gt_f32_e32 vcc, 1.0, v215
	s_waitcnt vmcnt(7)
	ds_write_b128 v191, v[128:131]
	s_waitcnt vmcnt(6)
	ds_write_b128 v202, v[136:139]
	s_waitcnt vmcnt(5)
	ds_write_b128 v190, v[132:135] offset:32768
	s_waitcnt vmcnt(4)
	ds_write_b128 v203, v[140:143] offset:32768
	s_cbranch_vccz .LBB0_203
	s_and_saveexec_b64 s[2:3], s[36:37]
	ds_write_b32 v186, v215 offset:128
	s_or_b64 exec, exec, s[2:3]
	s_waitcnt lgkmcnt(0)
	v_add_u32_e32 v161, v185, v192
	ds_read_b128 v[166:169], v161 offset:224
	ds_read_b128 v[170:173], v161 offset:192
	ds_read_b128 v[216:219], v161 offset:160
	ds_read_b128 v[220:223], v161 offset:128
	s_waitcnt lgkmcnt(3)
	v_pk_mul_f32 v[12:13], v[12:13], v[166:167]
	s_waitcnt lgkmcnt(2)
	v_pk_mul_f32 v[8:9], v[8:9], v[170:171]
	s_waitcnt lgkmcnt(1)
	v_pk_mul_f32 v[4:5], v[4:5], v[216:217]
	v_pk_mul_f32 v[14:15], v[14:15], v[168:169]
	v_pk_mul_f32 v[10:11], v[10:11], v[172:173]
	v_pk_mul_f32 v[6:7], v[6:7], v[218:219]
	s_waitcnt lgkmcnt(0)
	v_pk_mul_f32 v[2:3], v[2:3], v[222:223]
	v_pk_mul_f32 v[0:1], v[0:1], v[220:221]
	v_pk_mul_f32 v[60:61], v[60:61], v[166:167]
	v_pk_mul_f32 v[56:57], v[56:57], v[170:171]
	v_pk_mul_f32 v[52:53], v[52:53], v[216:217]
	v_pk_mul_f32 v[62:63], v[62:63], v[168:169]
	v_pk_mul_f32 v[58:59], v[58:59], v[172:173]
	v_pk_mul_f32 v[54:55], v[54:55], v[218:219]
	v_pk_mul_f32 v[50:51], v[50:51], v[222:223]
	v_pk_mul_f32 v[48:49], v[48:49], v[220:221]
	v_pk_mul_f32 v[44:45], v[44:45], v[166:167]
	v_pk_mul_f32 v[40:41], v[40:41], v[170:171]
	v_pk_mul_f32 v[36:37], v[36:37], v[216:217]
	v_pk_mul_f32 v[46:47], v[46:47], v[168:169]
	v_pk_mul_f32 v[42:43], v[42:43], v[172:173]
	v_pk_mul_f32 v[38:39], v[38:39], v[218:219]
	v_pk_mul_f32 v[34:35], v[34:35], v[222:223]
	v_pk_mul_f32 v[32:33], v[32:33], v[220:221]
	v_pk_mul_f32 v[28:29], v[28:29], v[166:167]
	v_pk_mul_f32 v[24:25], v[24:25], v[170:171]
	v_pk_mul_f32 v[20:21], v[20:21], v[216:217]
	v_pk_mul_f32 v[30:31], v[30:31], v[168:169]
	v_pk_mul_f32 v[26:27], v[26:27], v[172:173]
	v_pk_mul_f32 v[22:23], v[22:23], v[218:219]
	v_pk_mul_f32 v[18:19], v[18:19], v[222:223]
	v_pk_mul_f32 v[16:17], v[16:17], v[220:221]
; __device__ __forceinline__ void partialSM(f32x16& p0, f32x16& p1, float& m_reg, float& mn, float& alpha) {
;     ...
;   float mnC = -mn * C;
; #pragma unroll
;   for (int r = 0; r < 16; ++r) p0[r] = fmaf(p0[r], C, mnC);
; #pragma unroll
;   for (int r = 0; r < 16; ++r) p1[r] = fmaf(p1[r], C, mnC);
; #pragma unroll
;   for (int r = 0; r < 16; ++r) p0[r] = __builtin_amdgcn_exp2f(p0[r]);
; }
; __device__ __forceinline__ void finishSM(f32x16& p0, f32x16& p1, float alpha, float& l_reg, bf16x8& pa0, bf16x8& pa1, bf16x8& pa2, bf16x8& pa3) {
; #pragma unroll
;   for (int r = 0; r < 16; ++r) p1[r] = __builtin_amdgcn_exp2f(p1[r]);
;   float ps = 0;
; #pragma unroll
;   for (int r = 0; r < 16; ++r) ps += p0[r];
; #pragma unroll
;   for (int r = 0; r < 16; ++r) ps += p1[r];
;   { auto rr = __builtin_amdgcn_permlane32_swap(__float_as_uint(ps), __float_as_uint(ps), false, false);
;     ps = __uint_as_float(rr[0]) + __uint_as_float(rr[1]); }
;   l_reg = l_reg * alpha + ps;
;     ...
;   PK4(p0, 0, pa0); PK4(p0, 8, pa1); PK4(p1, 0, pa2); PK4(p1, 8, pa3);
;     ...
; }
; __device__ __forceinline__ void qkt(f32x16& p0, f32x16& p1, const char* Ks, const bf16x8* qr, int r32, int hi) {
;   p0 = f32x16{}; p1 = f32x16{};
; #pragma unroll
;   for (int d0 = 0; d0 < 8; ++d0) { int cb = (d0 * 16 + hi * 8) * 2;
;     bf16x8 b0 = *reinterpret_cast<const bf16x8*>(Ks + KSWZ(r32, cb));
;     bf16x8 b1 = *reinterpret_cast<const bf16x8*>(Ks + KSWZ(32 + r32, cb));
;     p0 = __builtin_amdgcn_mfma_f32_32x32x16_bf16(b0, qr[d0], p0, 0, 0, 0);
;     p1 = __builtin_amdgcn_mfma_f32_32x32x16_bf16(b1, qr[d0], p1, 0, 0, 0); }
.LBB0_203:
	v_cndmask_b32_e64 v216, v160, v164, s[0:1]
	v_mul_f32_e32 v217, 0xbe0293ee, v216
	v_fmamk_f32 v80, v80, 0x3e0293ee, v217
	v_fmamk_f32 v81, v81, 0x3e0293ee, v217
	v_fmamk_f32 v82, v82, 0x3e0293ee, v217
	v_fmamk_f32 v83, v83, 0x3e0293ee, v217
	v_fmamk_f32 v84, v84, 0x3e0293ee, v217
	v_fmamk_f32 v85, v85, 0x3e0293ee, v217
	v_fmamk_f32 v86, v86, 0x3e0293ee, v217
	v_fmamk_f32 v87, v87, 0x3e0293ee, v217
	v_fmamk_f32 v88, v88, 0x3e0293ee, v217
	v_fmamk_f32 v89, v89, 0x3e0293ee, v217
	v_fmamk_f32 v90, v90, 0x3e0293ee, v217
	v_fmamk_f32 v91, v91, 0x3e0293ee, v217
	v_fmamk_f32 v92, v92, 0x3e0293ee, v217
	v_fmamk_f32 v93, v93, 0x3e0293ee, v217
	v_fmamk_f32 v94, v94, 0x3e0293ee, v217
	v_fmamk_f32 v95, v95, 0x3e0293ee, v217
	v_exp_f32_e32 v160, v80
	v_exp_f32_e32 v161, v81
	v_exp_f32_e32 v162, v82
	v_exp_f32_e32 v173, v83
	v_exp_f32_e32 v174, v84
	v_exp_f32_e32 v175, v85
	v_exp_f32_e32 v163, v86
	v_exp_f32_e32 v172, v87
	v_exp_f32_e32 v164, v88
	v_exp_f32_e32 v165, v89
	v_exp_f32_e32 v170, v90
	v_exp_f32_e32 v171, v91
	v_exp_f32_e32 v166, v92
	v_exp_f32_e32 v167, v93
	v_exp_f32_e32 v168, v94
	v_exp_f32_e32 v169, v95
	v_fmamk_f32 v235, v64, 0x3e0293ee, v217
	v_fmamk_f32 v236, v65, 0x3e0293ee, v217
	v_fmamk_f32 v237, v66, 0x3e0293ee, v217
	v_fmamk_f32 v238, v67, 0x3e0293ee, v217
	v_fmamk_f32 v239, v68, 0x3e0293ee, v217
	v_fmamk_f32 v219, v69, 0x3e0293ee, v217
	v_fmamk_f32 v220, v70, 0x3e0293ee, v217
	v_fmamk_f32 v221, v71, 0x3e0293ee, v217
	v_fmamk_f32 v222, v72, 0x3e0293ee, v217
	v_fmamk_f32 v223, v73, 0x3e0293ee, v217
	v_fmamk_f32 v233, v74, 0x3e0293ee, v217
	v_fmamk_f32 v234, v75, 0x3e0293ee, v217
	v_fmamk_f32 v218, v76, 0x3e0293ee, v217
	v_fmamk_f32 v240, v77, 0x3e0293ee, v217
	v_fmamk_f32 v241, v78, 0x3e0293ee, v217
	v_fmac_f32_e32 v217, 0x3e0293ee, v79
	s_waitcnt lgkmcnt(0)
	s_barrier
	ds_read_b128 v[64:67], v204 offset:32768
	ds_read_b128 v[68:71], v204 offset:40960
	ds_read_b128 v[242:245], v211 offset:32768
	ds_read_b128 v[246:249], v211 offset:40960
	v_exp_f32_e32 v235, v235
	v_exp_f32_e32 v236, v236
	s_waitcnt lgkmcnt(3)
	v_mfma_f32_32x32x16_bf16 v[80:95], v[64:67], v[116:119], 0
	v_exp_f32_e32 v237, v237
	v_exp_f32_e32 v238, v238
	v_exp_f32_e32 v239, v239
	v_exp_f32_e32 v219, v219
	v_exp_f32_e32 v220, v220
	v_exp_f32_e32 v221, v221
	v_exp_f32_e32 v222, v222
	s_waitcnt lgkmcnt(2)
	v_mfma_f32_32x32x16_bf16 v[64:79], v[68:71], v[116:119], 0
	v_exp_f32_e32 v223, v223
	v_exp_f32_e32 v233, v233
	v_exp_f32_e32 v234, v234
	v_exp_f32_e32 v240, v240
	v_exp_f32_e32 v241, v241
	s_waitcnt lgkmcnt(1)
	v_mfma_f32_32x32x16_bf16 v[80:95], v[242:245], v[112:115], v[80:95]
	s_waitcnt lgkmcnt(0)
	v_mfma_f32_32x32x16_bf16 v[64:79], v[246:249], v[112:115], v[64:79]
	ds_read_b128 v[242:245], v210 offset:32768
	ds_read_b128 v[246:249], v210 offset:40960
	s_waitcnt lgkmcnt(1)
	v_mfma_f32_32x32x16_bf16 v[80:95], v[242:245], v[124:127], v[80:95]
	s_waitcnt lgkmcnt(0)
	v_mfma_f32_32x32x16_bf16 v[64:79], v[246:249], v[124:127], v[64:79]
	ds_read_b128 v[242:245], v208 offset:32768
	ds_read_b128 v[246:249], v208 offset:40960
	s_waitcnt lgkmcnt(1)
	v_mfma_f32_32x32x16_bf16 v[80:95], v[242:245], v[120:123], v[80:95]
	s_waitcnt lgkmcnt(0)
	v_mfma_f32_32x32x16_bf16 v[64:79], v[246:249], v[120:123], v[64:79]
	ds_read_b128 v[242:245], v206 offset:32768
	ds_read_b128 v[246:249], v206 offset:40960
	s_waitcnt lgkmcnt(1)
	v_mfma_f32_32x32x16_bf16 v[80:95], v[242:245], v[108:111], v[80:95]
	s_waitcnt lgkmcnt(0)
	v_mfma_f32_32x32x16_bf16 v[64:79], v[246:249], v[108:111], v[64:79]
	ds_read_b128 v[242:245], v205 offset:32768
	ds_read_b128 v[246:249], v205 offset:40960
	s_waitcnt lgkmcnt(1)
	v_mfma_f32_32x32x16_bf16 v[80:95], v[242:245], v[104:107], v[80:95]
	s_waitcnt lgkmcnt(0)
	v_mfma_f32_32x32x16_bf16 v[64:79], v[246:249], v[104:107], v[64:79]
	ds_read_b64_tr_b16 v[128:129], v188 offset:0
	ds_read_b64_tr_b16 v[130:131], v188 offset:0x800
	ds_read_b64_tr_b16 v[132:133], v188 offset:0x1000
	ds_read_b64_tr_b16 v[134:135], v188 offset:0x1800
	ds_read_b64_tr_b16 v[136:137], v188 offset:0x2000
	ds_read_b64_tr_b16 v[138:139], v188 offset:0x2800
	ds_read_b64_tr_b16 v[140:141], v188 offset:0x3000
	ds_read_b64_tr_b16 v[142:143], v188 offset:0x3800
	ds_read_b128 v[242:245], v207 offset:32768
	ds_read_b128 v[246:249], v207 offset:40960
	s_waitcnt lgkmcnt(1)
	v_mfma_f32_32x32x16_bf16 v[80:95], v[242:245], v[100:103], v[80:95]
	s_waitcnt lgkmcnt(0)
	v_mfma_f32_32x32x16_bf16 v[64:79], v[246:249], v[100:103], v[64:79]
	ds_read_b128 v[242:245], v209 offset:32768
	ds_read_b128 v[246:249], v209 offset:40960
	s_waitcnt lgkmcnt(1)
	v_mfma_f32_32x32x16_bf16 v[80:95], v[242:245], v[96:99], v[80:95]
	v_exp_f32_e32 v243, v217
	v_add_f32_e32 v217, v161, v160
	v_add_f32_e32 v217, v162, v217
	v_add_f32_e32 v217, v173, v217
	v_add_f32_e32 v217, v174, v217
	v_add_f32_e32 v217, v175, v217
	v_add_f32_e32 v217, v163, v217
	v_add_f32_e32 v217, v172, v217
	v_add_f32_e32 v217, v164, v217
	v_add_f32_e32 v217, v165, v217
	v_add_f32_e32 v217, v170, v217
	v_add_f32_e32 v217, v171, v217
	v_add_f32_e32 v217, v166, v217
	v_add_f32_e32 v217, v167, v217
	v_add_f32_e32 v217, v168, v217
	v_add_f32_e32 v217, v169, v217
	v_add_f32_e32 v217, v235, v217
	v_add_f32_e32 v217, v236, v217
	v_add_f32_e32 v217, v237, v217
	v_add_f32_e32 v217, v238, v217
	v_add_f32_e32 v217, v239, v217
	v_add_f32_e32 v217, v219, v217
	v_add_f32_e32 v217, v220, v217
	v_add_f32_e32 v217, v221, v217
	v_exp_f32_e32 v242, v218
	v_add_f32_e32 v217, v222, v217
	v_add_f32_e32 v217, v223, v217
	s_waitcnt lgkmcnt(0)
; #define SBAR() __builtin_amdgcn_sched_barrier(0)
; __device__ __forceinline__ void partialSM(f32x16& p0, f32x16& p1, float& m_reg, float& mn, float& alpha) {
;   constexpr float C = SCALE * 1.4426950408889634f;
;   float pmax = p0[0];
; #pragma unroll
;   for (int r = 1; r < 16; ++r) pmax = fmaxf(pmax, p0[r]);
; #pragma unroll
;   for (int r = 0; r < 16; ++r) pmax = fmaxf(pmax, p1[r]);
;   { auto rr = __builtin_amdgcn_permlane32_swap(__float_as_uint(pmax), __float_as_uint(pmax), false, false);
;     pmax = fmaxf(__uint_as_float(rr[0]), __uint_as_float(rr[1])); }
;   if (__builtin_expect(__all(pmax - m_reg <= THR / SCALE), 1)) { mn = m_reg; alpha = 1.f; }
;   else { mn = fmaxf(m_reg, pmax); alpha = __builtin_amdgcn_exp2f((m_reg - mn) * C); m_reg = mn; }
; template <int D0> __device__ __forceinline__ void pv_one(f32x16& od, int vb, bf16x8 pa0, bf16x8 pa1, bf16x8 pa2, bf16x8 pa3) {
;   const s16x4 l0 = tr_read<v_rd_off(D0, 0, 0)>(vb), h0 = tr_read<v_rd_off(D0, 0, 1)>(vb), l1 = tr_read<v_rd_off(D0, 1, 0)>(vb), h1 = tr_read<v_rd_off(D0, 1, 1)>(vb);
;   const s16x4 l2 = tr_read<v_rd_off(D0, 2, 0)>(vb), h2 = tr_read<v_rd_off(D0, 2, 1)>(vb), l3 = tr_read<v_rd_off(D0, 3, 0)>(vb), h3 = tr_read<v_rd_off(D0, 3, 1)>(vb);
;   asm volatile("s_waitcnt lgkmcnt(0)" ::: "memory"); SBAR();
;     ...
;   od = __builtin_amdgcn_mfma_f32_32x32x16_bf16(pa0, PK(l0, h0), od, 0, 0, 0);
;   od = __builtin_amdgcn_mfma_f32_32x32x16_bf16(pa1, PK(l1, h1), od, 0, 0, 0);
;   od = __builtin_amdgcn_mfma_f32_32x32x16_bf16(pa2, PK(l2, h2), od, 0, 0, 0);
;   od = __builtin_amdgcn_mfma_f32_32x32x16_bf16(pa3, PK(l3, h3), od, 0, 0, 0);
;     ...
; }
; __device__ __forceinline__ void pv_d0(f32x16* o, int vb, bf16x8 pa0, bf16x8 pa1, bf16x8 pa2, bf16x8 pa3) {
;   pv_one<0>(o[0], vb, pa0, pa1, pa2, pa3); pv_one<1>(o[1], vb, pa0, pa1, pa2, pa3); pv_one<2>(o[2], vb, pa0, pa1, pa2, pa3); pv_one<3>(o[3], vb, pa0, pa1, pa2, pa3);
	v_mfma_f32_32x32x16_bf16 v[64:79], v[246:249], v[96:99], v[64:79]
	v_add_f32_e32 v217, v233, v217
	v_add_f32_e32 v217, v234, v217
	v_add_f32_e32 v217, v242, v217
	v_add_f32_e32 v217, v240, v217
	v_add_f32_e32 v217, v241, v217
	v_add_f32_e32 v217, v243, v217
	v_mov_b32_e32 v218, v217
	v_cvt_pk_bf16_f32 v160, v160, v161
	v_cvt_pk_bf16_f32 v161, v162, v173
	v_cvt_pk_bf16_f32 v162, v174, v175
	v_cvt_pk_bf16_f32 v163, v163, v172
	v_cvt_pk_bf16_f32 v164, v164, v165
	v_cvt_pk_bf16_f32 v165, v170, v171
	v_cvt_pk_bf16_f32 v166, v166, v167
	v_cvt_pk_bf16_f32 v167, v168, v169
	v_cvt_pk_bf16_f32 v168, v235, v236
	v_cvt_pk_bf16_f32 v169, v237, v238
	v_cvt_pk_bf16_f32 v170, v239, v219
	v_cvt_pk_bf16_f32 v171, v220, v221
	v_cvt_pk_bf16_f32 v172, v222, v223
	v_cvt_pk_bf16_f32 v173, v233, v234
	v_cvt_pk_bf16_f32 v174, v242, v240
	v_cvt_pk_bf16_f32 v175, v241, v243
	v_permlane32_swap_b32_e32 v217, v218
	v_permlane32_swap_b32_e32 v160, v162
	v_permlane32_swap_b32_e32 v161, v163
	v_permlane32_swap_b32_e32 v164, v166
	v_permlane32_swap_b32_e32 v165, v167
	v_permlane32_swap_b32_e32 v168, v170
	v_permlane32_swap_b32_e32 v169, v171
	v_permlane32_swap_b32_e32 v172, v174
	v_permlane32_swap_b32_e32 v173, v175
	s_waitcnt lgkmcnt(0)
	s_nop 0
	v_mfma_f32_32x32x16_bf16 v[0:15], v[160:163], v[128:131], v[0:15]
	ds_read_b64_tr_b16 v[220:221], v188 offset:0x200
	ds_read_b64_tr_b16 v[222:223], v188 offset:0xa00
	v_mfma_f32_32x32x16_bf16 v[0:15], v[164:167], v[132:135], v[0:15]
	ds_read_b64_tr_b16 v[234:235], v188 offset:0x1200
	ds_read_b64_tr_b16 v[236:237], v188 offset:0x1a00
	v_mfma_f32_32x32x16_bf16 v[0:15], v[168:171], v[136:139], v[0:15]
	ds_read_b64_tr_b16 v[238:239], v188 offset:0x2200
	ds_read_b64_tr_b16 v[240:241], v188 offset:0x2a00
	v_mfma_f32_32x32x16_bf16 v[0:15], v[172:175], v[140:143], v[0:15]
	ds_read_b64_tr_b16 v[242:243], v188 offset:0x3200
	ds_read_b64_tr_b16 v[244:245], v188 offset:0x3a00
	s_cmpk_gt_u32 s20, 0x7c
	s_cselect_b64 s[2:3], -1, 0
	s_and_b64 vcc, exec, s[2:3]
	s_cbranch_vccnz .Lgq_noprefetch
	global_load_dwordx4 v[128:131], v178, s[6:7]
	global_load_dwordx4 v[132:135], v178, s[4:5]
	global_load_dwordx4 v[136:139], v179, s[6:7]
	global_load_dwordx4 v[140:143], v179, s[4:5]
.LBB0_205:
	s_add_u32 s6, s6, 0x4000
	s_addc_u32 s7, s7, 0
	s_add_u32 s4, s4, 0x4000
	s_addc_u32 s5, s5, 0
	s_waitcnt lgkmcnt(0)
	v_mfma_f32_32x32x16_bf16 v[48:63], v[160:163], v[220:223], v[48:63]
	ds_read_b64_tr_b16 v[220:221], v188 offset:0x400
	ds_read_b64_tr_b16 v[222:223], v188 offset:0xc00
	v_mfma_f32_32x32x16_bf16 v[48:63], v[164:167], v[234:237], v[48:63]
	ds_read_b64_tr_b16 v[234:235], v188 offset:0x1400
	ds_read_b64_tr_b16 v[236:237], v188 offset:0x1c00
	v_mfma_f32_32x32x16_bf16 v[48:63], v[168:171], v[238:241], v[48:63]
	ds_read_b64_tr_b16 v[238:239], v188 offset:0x2400
	ds_read_b64_tr_b16 v[240:241], v188 offset:0x2c00
	v_mfma_f32_32x32x16_bf16 v[48:63], v[172:175], v[242:245], v[48:63]
	ds_read_b64_tr_b16 v[242:243], v188 offset:0x3400
	ds_read_b64_tr_b16 v[244:245], v188 offset:0x3c00
	s_waitcnt lgkmcnt(0)
	v_mfma_f32_32x32x16_bf16 v[32:47], v[160:163], v[220:223], v[32:47]
	ds_read_b64_tr_b16 v[220:221], v188 offset:0x600
	ds_read_b64_tr_b16 v[222:223], v188 offset:0xe00
	v_mfma_f32_32x32x16_bf16 v[32:47], v[164:167], v[234:237], v[32:47]
	ds_read_b64_tr_b16 v[234:235], v188 offset:0x1600
	ds_read_b64_tr_b16 v[236:237], v188 offset:0x1e00
	v_mfma_f32_32x32x16_bf16 v[32:47], v[168:171], v[238:241], v[32:47]
	ds_read_b64_tr_b16 v[238:239], v188 offset:0x2600
	ds_read_b64_tr_b16 v[240:241], v188 offset:0x2e00
	v_mfma_f32_32x32x16_bf16 v[32:47], v[172:175], v[242:245], v[32:47]
	ds_read_b64_tr_b16 v[242:243], v188 offset:0x3600
	ds_read_b64_tr_b16 v[244:245], v188 offset:0x3e00
	s_waitcnt lgkmcnt(0)
	v_mfma_f32_32x32x16_bf16 v[16:31], v[160:163], v[220:223], v[16:31]
	v_max_f32_e32 v160, v80, v81
	v_max3_f32 v160, v160, v82, v83
	v_max3_f32 v160, v160, v84, v85
	v_max3_f32 v160, v160, v86, v87
	v_max3_f32 v160, v160, v88, v89
	v_max3_f32 v160, v160, v90, v91
	v_max3_f32 v160, v160, v92, v93
	v_mfma_f32_32x32x16_bf16 v[16:31], v[164:167], v[234:237], v[16:31]
	v_max3_f32 v160, v160, v94, v95
	v_max3_f32 v160, v160, v64, v65
	v_max3_f32 v160, v160, v66, v67
	v_max3_f32 v160, v160, v68, v69
	v_max3_f32 v160, v160, v70, v71
	v_max3_f32 v160, v160, v72, v73
	v_max3_f32 v160, v160, v74, v75
	v_max3_f32 v160, v160, v76, v77
	v_mfma_f32_32x32x16_bf16 v[16:31], v[168:171], v[238:241], v[16:31]
	v_max3_f32 v160, v160, v78, v79
	v_mov_b32_e32 v161, v160
	s_nop 1
	v_permlane32_swap_b32_e32 v160, v161
	v_max_f32_e32 v160, v160, v161
	v_sub_f32_e32 v161, v160, v216
	v_cmp_ge_f32_e32 vcc, s18, v161
	v_max_f32_e32 v161, v216, v160
	v_mfma_f32_32x32x16_bf16 v[16:31], v[172:175], v[242:245], v[16:31]
	v_sub_f32_e32 v160, v216, v161
	v_mul_f32_e32 v160, 0x3e0293ee, v160
	v_exp_f32_e32 v160, v160
	s_cmp_eq_u64 vcc, exec
	s_cselect_b64 s[0:1], -1, 0
	s_barrier
	s_waitcnt vmcnt(4)
	v_cndmask_b32_e64 v160, v160, 1.0, s[0:1]
	v_cmp_gt_f32_e32 vcc, 1.0, v160
	ds_write_b128 v191, v[144:147] offset:16384
	ds_write_b128 v202, v[148:151] offset:16384
	ds_write_b128 v190, v[152:155] offset:49152
	ds_write_b128 v203, v[156:159] offset:49152
	s_cbranch_vccz .LBB0_209
	s_and_saveexec_b64 s[42:43], s[36:37]
	ds_write_b32 v186, v160 offset:128
	s_or_b64 exec, exec, s[42:43]
	s_waitcnt lgkmcnt(0)
	v_add_u32_e32 v156, v185, v192
	ds_read_b128 v[144:147], v156 offset:224
	ds_read_b128 v[148:151], v156 offset:192
	ds_read_b128 v[152:155], v156 offset:160
	ds_read_b128 v[156:159], v156 offset:128
	s_waitcnt lgkmcnt(3)
	v_pk_mul_f32 v[12:13], v[12:13], v[144:145]
	s_waitcnt lgkmcnt(2)
	v_pk_mul_f32 v[8:9], v[8:9], v[148:149]
	s_waitcnt lgkmcnt(1)
	v_pk_mul_f32 v[4:5], v[4:5], v[152:153]
	v_pk_mul_f32 v[14:15], v[14:15], v[146:147]
	v_pk_mul_f32 v[10:11], v[10:11], v[150:151]
	v_pk_mul_f32 v[6:7], v[6:7], v[154:155]
	s_waitcnt lgkmcnt(0)
	v_pk_mul_f32 v[2:3], v[2:3], v[158:159]
	v_pk_mul_f32 v[0:1], v[0:1], v[156:157]
	v_pk_mul_f32 v[60:61], v[60:61], v[144:145]
	v_pk_mul_f32 v[56:57], v[56:57], v[148:149]
	v_pk_mul_f32 v[52:53], v[52:53], v[152:153]
	v_pk_mul_f32 v[62:63], v[62:63], v[146:147]
	v_pk_mul_f32 v[58:59], v[58:59], v[150:151]
	v_pk_mul_f32 v[54:55], v[54:55], v[154:155]
	v_pk_mul_f32 v[50:51], v[50:51], v[158:159]
	v_pk_mul_f32 v[48:49], v[48:49], v[156:157]
	v_pk_mul_f32 v[44:45], v[44:45], v[144:145]
	v_pk_mul_f32 v[40:41], v[40:41], v[148:149]
	v_pk_mul_f32 v[36:37], v[36:37], v[152:153]
	v_pk_mul_f32 v[46:47], v[46:47], v[146:147]
	v_pk_mul_f32 v[42:43], v[42:43], v[150:151]
	v_pk_mul_f32 v[38:39], v[38:39], v[154:155]
	v_pk_mul_f32 v[34:35], v[34:35], v[158:159]
	v_pk_mul_f32 v[32:33], v[32:33], v[156:157]
	v_pk_mul_f32 v[28:29], v[28:29], v[144:145]
	v_pk_mul_f32 v[24:25], v[24:25], v[148:149]
	v_pk_mul_f32 v[20:21], v[20:21], v[152:153]
	v_pk_mul_f32 v[30:31], v[30:31], v[146:147]
	v_pk_mul_f32 v[26:27], v[26:27], v[150:151]
	v_pk_mul_f32 v[22:23], v[22:23], v[154:155]
	v_pk_mul_f32 v[18:19], v[18:19], v[158:159]
	v_pk_mul_f32 v[16:17], v[16:17], v[156:157]

; #define SLOAD(i, k0) do { sr_[i].vs0 = *(const bf16x8*)(&Vh[(long)((k0) + sr) * LDK + sc]); sr_[i].vs1 = *(const bf16x8*)(&Vh[(long)((k0) + 32 + sr) * LDK + sc]); \
;     sr_[i].ks0 = *(const bf16x8*)(&Kh[(long)((k0) + sr) * LDK + sc]); sr_[i].ks1 = *(const bf16x8*)(&Kh[(long)((k0) + 32 + sr) * LDK + sc]); } while (0)
; #define SWRITE(b, i) do { *(bf16x8*)(V_lds + (b) * SHM_V + vst0) = sr_[i].vs0;          \
;     *(bf16x8*)(V_lds + (b) * SHM_V + vst1) = sr_[i].vs1; int kc = sc * 2;               \
;     *(bf16x8*)(K_lds + (b) * SHM_K + KSWZ(sr, kc)) = sr_[i].ks0;                       \
;     *(bf16x8*)(K_lds + (b) * SHM_K + KSWZ(32 + sr, kc)) = sr_[i].ks1; } while (0)
; template <int MODE>
; __device__ __forceinline__ void amask(f32x16& p0, f32x16& p1, int j, const Unit& U, int wid, int r32, int hi, const float* tbl) {
;     ...
;     const int qrow = U.qr + (wid >> 1), kr = U.kr0 + j, st = min(max(qrow - 4, 0), 120);
;     if (kr < st || kr >= st + 8) {
; #pragma unroll
;       for (int r = 0; r < 16; ++r) { p0[r] = NEG; p1[r] = NEG; }
;     } else {
;       const int jq = (wid & 1) * 32 + r32, cs = min(max(jq - 8, 0), 48);
;       const float* tr = tbl + (kr - qrow + 7) * 31 + (15 - jq);
; template <int MODE, int SDEPTH, bool SIMPLE>
; __device__ __forceinline__ void attn_body(const Unit& U, char* lds, const int tid) {
;     ...
;     for (int j = 0; j < NT; ++j) {
;       asm volatile("s_waitcnt vmcnt(0)" ::: "memory"); __syncthreads(); SWRITE(0, 0);
;       if (j + 1 < NT) SLOAD(0, (j + 1) * KVBLK);
.LBB0_288:
	s_or_b64 exec, exec, s[8:9]
	s_add_i32 s28, s28, 1
	s_mov_b64 s[8:9], 0x230000
	v_add_u32_e32 v162, 0x7c, v162
	s_cmp_eq_u32 s25, s28
	v_lshl_add_u64 v[152:153], v[152:153], 0, s[8:9]
	s_cbranch_scc1 .LBB0_296
	.p2align	6

; __device__ __forceinline__ int crow(int r, int hi) { return (r & 3) + 8 * (r >> 2) + 4 * hi; }
; template <int MODE>
; __device__ __forceinline__ void amask(f32x16& p0, f32x16& p1, int j, const Unit& U, int wid, int r32, int hi, const float* tbl) {
;   if constexpr (MODE == 1) {
;     const int qrow = U.qr + (wid >> 1), kr = U.kr0 + j, st = min(max(qrow - 4, 0), 120);
;     if (kr < st || kr >= st + 8) {
; #pragma unroll
;       for (int r = 0; r < 16; ++r) { p0[r] = NEG; p1[r] = NEG; }
;     } else {
;       const int jq = (wid & 1) * 32 + r32, cs = min(max(jq - 8, 0), 48);
;       const float* tr = tbl + (kr - qrow + 7) * 31 + (15 - jq);
; #pragma unroll
;       for (int r2 = 0; r2 < 8; ++r2) {
;         float b0[2], b1[2];
; #pragma unroll
;         for (int q = 0; q < 2; ++q) { const int c = crow(r2 * 2 + q, hi); b0[q] = tr[c]; b1[q] = tr[c + 32]; }
;         asm volatile("" ::: "memory");
; #pragma unroll
;         for (int q = 0; q < 2; ++q) { const int r = r2 * 2 + q, c = crow(r, hi);
;           p0[r] = ((unsigned)(c - cs) < 16u) ? p0[r] + b0[q] : NEG;
;           p1[r] = ((unsigned)(c + 32 - cs) < 16u) ? p1[r] + b1[q] : NEG; }
;       }
; template <int MODE, int SDEPTH, bool SIMPLE>
; __device__ __forceinline__ void attn_body(const Unit& U, char* lds, const int tid) {
;     ...
;       __syncthreads();
;       bool act = true;
;       if constexpr (MODE == 1) { const int qrow = U.qr + (wid >> 1), kr = U.kr0 + j, st = min(max(qrow - 4, 0), 120); act = (kr >= st) && (kr < st + 8); }
;       if constexpr (MODE == 2) { const int q0 = U.i0 + wid * 32, t0 = U.k0 + j * 64; act = (t0 + 63 >= q0 - 64) && (t0 <= q0 + 31 + 64); }
;       if (act) {
;         qkt(p0, p1, K_lds, qr, r32, hi); amask<MODE>(p0, p1, j, U, wid, r32, hi, tbl);
.LBB0_291:
	s_add_i32 s8, s15, s28
	s_add_i32 s36, s8, -4
	v_cmp_ge_u32_e64 s[8:9], s36, v160
	v_cmp_lt_u32_e32 vcc, s36, v161
	s_and_b64 vcc, s[8:9], vcc
	s_waitcnt lgkmcnt(0)
	s_barrier
	s_and_saveexec_b64 s[8:9], vcc
	s_cbranch_execz .LBB0_288
	ds_read_b128 v[66:69], v168 offset:32768
	ds_read_b128 v[70:73], v168 offset:40960
	ds_read_b128 v[176:179], v169 offset:32768
	ds_read_b128 v[180:183], v169 offset:40960
	s_waitcnt lgkmcnt(3)
	v_mfma_f32_32x32x16_bf16 v[82:97], v[66:69], v[98:101], 0
	s_waitcnt lgkmcnt(2)
	v_mfma_f32_32x32x16_bf16 v[66:81], v[70:73], v[98:101], 0
	s_waitcnt lgkmcnt(1)
	v_mfma_f32_32x32x16_bf16 v[82:97], v[176:179], v[102:105], v[82:97]
	s_waitcnt lgkmcnt(0)
	v_mfma_f32_32x32x16_bf16 v[66:81], v[180:183], v[102:105], v[66:81]
	ds_read_b128 v[176:179], v170 offset:32768
	ds_read_b128 v[180:183], v170 offset:40960
	s_waitcnt lgkmcnt(1)
	v_mfma_f32_32x32x16_bf16 v[82:97], v[176:179], v[106:109], v[82:97]
	s_waitcnt lgkmcnt(0)
	v_mfma_f32_32x32x16_bf16 v[66:81], v[180:183], v[106:109], v[66:81]
	ds_read_b128 v[176:179], v171 offset:32768
	ds_read_b128 v[180:183], v171 offset:40960
	s_waitcnt lgkmcnt(1)
	v_mfma_f32_32x32x16_bf16 v[82:97], v[176:179], v[110:113], v[82:97]
	s_waitcnt lgkmcnt(0)
	v_mfma_f32_32x32x16_bf16 v[66:81], v[180:183], v[110:113], v[66:81]
	ds_read_b128 v[176:179], v172 offset:32768
	ds_read_b128 v[180:183], v172 offset:40960
	s_waitcnt lgkmcnt(1)
	v_mfma_f32_32x32x16_bf16 v[82:97], v[176:179], v[114:117], v[82:97]
	s_waitcnt lgkmcnt(0)
	v_mfma_f32_32x32x16_bf16 v[66:81], v[180:183], v[114:117], v[66:81]
	ds_read_b128 v[176:179], v173 offset:32768
	ds_read_b128 v[180:183], v173 offset:40960
	s_waitcnt lgkmcnt(1)
	v_mfma_f32_32x32x16_bf16 v[82:97], v[176:179], v[118:121], v[82:97]
	s_waitcnt lgkmcnt(0)
	v_mfma_f32_32x32x16_bf16 v[66:81], v[180:183], v[118:121], v[66:81]
	ds_read_b128 v[176:179], v174 offset:32768
	ds_read_b128 v[180:183], v174 offset:40960
	s_waitcnt lgkmcnt(1)
	v_mfma_f32_32x32x16_bf16 v[82:97], v[176:179], v[122:125], v[82:97]
	s_waitcnt lgkmcnt(0)
	v_mfma_f32_32x32x16_bf16 v[66:81], v[180:183], v[122:125], v[66:81]
	ds_read_b128 v[176:179], v175 offset:32768
	ds_read_b128 v[180:183], v175 offset:40960
	s_waitcnt lgkmcnt(1)
	v_mfma_f32_32x32x16_bf16 v[82:97], v[176:179], v[126:129], v[82:97]
	ds_read2_b32 v[176:177], v162 offset1:1
	ds_read2_b32 v[178:179], v162 offset0:32 offset1:33
	s_waitcnt lgkmcnt(2)
	v_mfma_f32_32x32x16_bf16 v[66:81], v[180:183], v[126:129], v[66:81]
	ds_read2_b32 v[180:181], v162 offset0:2 offset1:3
	ds_read2_b32 v[182:183], v162 offset0:34 offset1:35
	ds_read2_b32 v[184:185], v162 offset0:8 offset1:9
	ds_read2_b32 v[186:187], v162 offset0:40 offset1:41
	s_waitcnt lgkmcnt(5)
	s_nop 2
	v_add_f32_e32 v82, v82, v176
	v_cndmask_b32_e64 v176, v230, v82, s[40:41]
	v_add_f32_e32 v82, v83, v177
	ds_read2_b32 v[188:189], v162 offset0:10 offset1:11
	ds_read2_b32 v[190:191], v162 offset0:42 offset1:43
	v_cndmask_b32_e64 v83, v230, v82, s[44:45]
	s_waitcnt lgkmcnt(5)
	v_add_f32_e32 v82, v84, v180
	v_cndmask_b32_e64 v84, v230, v82, s[48:49]
	v_add_f32_e32 v82, v85, v181
	ds_read2_b32 v[202:203], v162 offset0:16 offset1:17
	ds_read2_b32 v[204:205], v162 offset0:48 offset1:49
	v_cndmask_b32_e64 v85, v230, v82, s[52:53]
	s_waitcnt lgkmcnt(5)
	v_add_f32_e32 v82, v86, v184
	v_cndmask_b32_e64 v86, v230, v82, s[56:57]
	v_add_f32_e32 v82, v87, v185
	ds_read2_b32 v[206:207], v162 offset0:18 offset1:19
	ds_read2_b32 v[208:209], v162 offset0:50 offset1:51
	v_cndmask_b32_e64 v87, v230, v82, s[60:61]
	s_waitcnt lgkmcnt(5)
	v_add_f32_e32 v82, v88, v188
	v_cndmask_b32_e64 v88, v230, v82, s[64:65]
	v_add_f32_e32 v82, v89, v189
	ds_read2_b32 v[210:211], v162 offset0:24 offset1:25
	ds_read2_b32 v[212:213], v162 offset0:56 offset1:57
	v_cndmask_b32_e64 v89, v230, v82, s[68:69]
	s_waitcnt lgkmcnt(5)
	v_add_f32_e32 v82, v90, v202
	v_cndmask_b32_e64 v90, v230, v82, s[72:73]
	v_add_f32_e32 v82, v91, v203
	ds_read2_b32 v[214:215], v162 offset0:26 offset1:27
	ds_read2_b32 v[216:217], v162 offset0:58 offset1:59
	v_cndmask_b32_e64 v91, v230, v82, s[76:77]
	s_waitcnt lgkmcnt(5)
	v_add_f32_e32 v82, v92, v206
	v_cndmask_b32_e64 v92, v230, v82, s[80:81]
	v_add_f32_e32 v82, v93, v207
	v_cndmask_b32_e64 v93, v230, v82, s[84:85]
	s_waitcnt lgkmcnt(3)
	v_add_f32_e32 v82, v94, v210
	v_cndmask_b32_e64 v94, v230, v82, s[88:89]
	v_add_f32_e32 v82, v95, v211
	v_cndmask_b32_e64 v95, v230, v82, s[92:93]
	s_waitcnt lgkmcnt(1)
	v_add_f32_e32 v82, v96, v214
	v_cndmask_b32_e64 v96, v230, v82, s[96:97]
	v_add_f32_e32 v82, v97, v215
	v_cndmask_b32_e64 v97, v230, v82, s[0:1]
	v_max_f32_e32 v82, v176, v83
	v_max3_f32 v82, v82, v84, v85
	v_max3_f32 v82, v82, v86, v87
	v_max3_f32 v82, v82, v88, v89
	v_max3_f32 v82, v82, v90, v91
	v_max3_f32 v82, v82, v92, v93
	v_add_f32_e32 v66, v66, v178
	v_add_f32_e32 v67, v67, v179
	v_max3_f32 v82, v82, v94, v95
	v_cndmask_b32_e64 v66, v230, v66, s[42:43]
	v_cndmask_b32_e64 v67, v230, v67, s[46:47]
	v_add_f32_e32 v68, v68, v182
	v_add_f32_e32 v69, v69, v183
	v_max3_f32 v82, v82, v96, v97
	v_cndmask_b32_e64 v68, v230, v68, s[50:51]
	v_cndmask_b32_e64 v69, v230, v69, s[54:55]
	v_add_f32_e32 v70, v70, v186
	v_add_f32_e32 v71, v71, v187
	v_max3_f32 v82, v82, v66, v67
	v_cndmask_b32_e64 v70, v230, v70, s[58:59]
	v_cndmask_b32_e64 v71, v230, v71, s[62:63]
	v_add_f32_e32 v72, v72, v190
	v_add_f32_e32 v73, v73, v191
	v_max3_f32 v82, v82, v68, v69
	v_cndmask_b32_e64 v72, v230, v72, s[66:67]
	v_cndmask_b32_e64 v73, v230, v73, s[70:71]
	v_add_f32_e32 v74, v74, v204
	v_add_f32_e32 v75, v75, v205
	v_max3_f32 v82, v82, v70, v71
	v_cndmask_b32_e64 v74, v230, v74, s[74:75]
	v_cndmask_b32_e64 v75, v230, v75, s[78:79]
	v_add_f32_e32 v76, v76, v208
	v_add_f32_e32 v77, v77, v209
	v_max3_f32 v82, v82, v72, v73
	v_cndmask_b32_e64 v76, v230, v76, s[82:83]
	v_cndmask_b32_e64 v77, v230, v77, s[86:87]
	v_add_f32_e32 v78, v78, v212
	v_add_f32_e32 v79, v79, v213
	v_max3_f32 v82, v82, v74, v75
	s_waitcnt lgkmcnt(0)
; __device__ __forceinline__ void partialSM(f32x16& p0, f32x16& p1, float& m_reg, float& mn, float& alpha) {
;   constexpr float C = SCALE * 1.4426950408889634f;
;   float pmax = p0[0];
; #pragma unroll
;   for (int r = 1; r < 16; ++r) pmax = fmaxf(pmax, p0[r]);
; #pragma unroll
;   for (int r = 0; r < 16; ++r) pmax = fmaxf(pmax, p1[r]);
;   { auto rr = __builtin_amdgcn_permlane32_swap(__float_as_uint(pmax), __float_as_uint(pmax), false, false);
;     pmax = fmaxf(__uint_as_float(rr[0]), __uint_as_float(rr[1])); }
;   if (__builtin_expect(__all(pmax - m_reg <= THR / SCALE), 1)) { mn = m_reg; alpha = 1.f; }
;   else { mn = fmaxf(m_reg, pmax); alpha = __builtin_amdgcn_exp2f((m_reg - mn) * C); m_reg = mn; }
;   float mnC = -mn * C;
; #pragma unroll
;   for (int r = 0; r < 16; ++r) p0[r] = fmaf(p0[r], C, mnC);
; #pragma unroll
;   for (int r = 0; r < 16; ++r) p1[r] = fmaf(p1[r], C, mnC);
; #pragma unroll
;   for (int r = 0; r < 16; ++r) p0[r] = __builtin_amdgcn_exp2f(p0[r]);
; }
; __device__ __forceinline__ void finishSM(f32x16& p0, f32x16& p1, float alpha, float& l_reg, bf16x8& pa0, bf16x8& pa1, bf16x8& pa2, bf16x8& pa3) {
; #pragma unroll
;   for (int r = 0; r < 16; ++r) p1[r] = __builtin_amdgcn_exp2f(p1[r]);
;   float ps = 0;
; #pragma unroll
;   for (int r = 0; r < 16; ++r) ps += p0[r];
; #pragma unroll
;   for (int r = 0; r < 16; ++r) ps += p1[r];
;   { auto rr = __builtin_amdgcn_permlane32_swap(__float_as_uint(ps), __float_as_uint(ps), false, false);
;     ps = __uint_as_float(rr[0]) + __uint_as_float(rr[1]); }
;   l_reg = l_reg * alpha + ps;
;     ...
;   PK4(p0, 0, pa0); PK4(p0, 8, pa1); PK4(p1, 0, pa2); PK4(p1, 8, pa3);
;     ...
; }
	v_add_f32_e32 v81, v81, v217
	v_cndmask_b32_e64 v78, v230, v78, s[90:91]
	v_cndmask_b32_e64 v79, v230, v79, s[94:95]
	v_add_f32_e32 v80, v80, v216
	v_max3_f32 v82, v82, v76, v77
	v_cndmask_b32_e64 v81, v230, v81, s[4:5]
	v_cndmask_b32_e64 v80, v230, v80, s[98:99]
	v_max3_f32 v82, v82, v78, v79
	v_max3_f32 v82, v82, v80, v81
	v_mov_b32_e32 v177, v82
	s_nop 1
	v_permlane32_swap_b32_e32 v82, v177
	v_max_f32_e32 v82, v82, v177
	v_sub_f32_e32 v177, v82, v163
	v_cmp_ge_f32_e32 vcc, s18, v177
	v_max_f32_e32 v82, v163, v82
	v_sub_f32_e32 v177, v163, v82
	v_mul_f32_e32 v177, 0x3e0293ee, v177
	v_exp_f32_e32 v177, v177
	s_cmp_eq_u64 vcc, exec
	s_cselect_b64 vcc, -1, 0
	v_cndmask_b32_e32 v163, v82, v163, vcc
	v_cndmask_b32_e64 v82, v177, 1.0, vcc
	v_mul_f32_e32 v177, 0xbe0293ee, v163
	v_fmamk_f32 v176, v176, 0x3e0293ee, v177
	v_fmamk_f32 v83, v83, 0x3e0293ee, v177
	v_fmamk_f32 v84, v84, 0x3e0293ee, v177
	v_fmamk_f32 v85, v85, 0x3e0293ee, v177
	v_fmamk_f32 v86, v86, 0x3e0293ee, v177
	v_fmamk_f32 v87, v87, 0x3e0293ee, v177
	v_fmamk_f32 v88, v88, 0x3e0293ee, v177
	v_fmamk_f32 v89, v89, 0x3e0293ee, v177
	v_fmamk_f32 v90, v90, 0x3e0293ee, v177
	v_fmamk_f32 v91, v91, 0x3e0293ee, v177
	v_fmamk_f32 v92, v92, 0x3e0293ee, v177
	v_fmamk_f32 v93, v93, 0x3e0293ee, v177
	v_fmamk_f32 v94, v94, 0x3e0293ee, v177
	v_fmamk_f32 v95, v95, 0x3e0293ee, v177
	v_fmamk_f32 v96, v96, 0x3e0293ee, v177
	v_fmamk_f32 v97, v97, 0x3e0293ee, v177
	v_fmamk_f32 v66, v66, 0x3e0293ee, v177
	v_fmamk_f32 v67, v67, 0x3e0293ee, v177
	v_fmamk_f32 v68, v68, 0x3e0293ee, v177
	v_fmamk_f32 v69, v69, 0x3e0293ee, v177
	v_fmamk_f32 v70, v70, 0x3e0293ee, v177
	v_fmamk_f32 v71, v71, 0x3e0293ee, v177
	v_fmamk_f32 v72, v72, 0x3e0293ee, v177
	v_fmamk_f32 v73, v73, 0x3e0293ee, v177
	v_fmamk_f32 v74, v74, 0x3e0293ee, v177
	v_fmamk_f32 v75, v75, 0x3e0293ee, v177
	v_fmamk_f32 v76, v76, 0x3e0293ee, v177
	v_fmamk_f32 v77, v77, 0x3e0293ee, v177
	v_fmamk_f32 v78, v78, 0x3e0293ee, v177
	v_fmamk_f32 v79, v79, 0x3e0293ee, v177
	v_fmamk_f32 v80, v80, 0x3e0293ee, v177
	v_fmac_f32_e32 v177, 0x3e0293ee, v81
	v_exp_f32_e32 v81, v176
	v_exp_f32_e32 v176, v83
	v_exp_f32_e32 v178, v84
	v_exp_f32_e32 v85, v85
	v_exp_f32_e32 v86, v86
	v_exp_f32_e32 v179, v66
	v_exp_f32_e32 v87, v87
	v_add_f32_e32 v66, v176, v81
	v_exp_f32_e32 v88, v88
	v_add_f32_e32 v66, v178, v66
	v_exp_f32_e32 v89, v89
	v_add_f32_e32 v66, v85, v66
	v_exp_f32_e32 v90, v90
	v_add_f32_e32 v66, v86, v66
	v_exp_f32_e32 v91, v91
	v_add_f32_e32 v66, v87, v66
	v_exp_f32_e32 v92, v92
	v_add_f32_e32 v66, v88, v66
	v_exp_f32_e32 v93, v93
	v_add_f32_e32 v66, v89, v66
	v_exp_f32_e32 v94, v94
	v_add_f32_e32 v66, v90, v66
	v_exp_f32_e32 v95, v95
	v_add_f32_e32 v66, v91, v66
	v_exp_f32_e32 v96, v96
	v_add_f32_e32 v66, v92, v66
	v_exp_f32_e32 v97, v97
	v_add_f32_e32 v66, v93, v66
	v_add_f32_e32 v66, v94, v66
	v_exp_f32_e32 v180, v67
	v_add_f32_e32 v66, v95, v66
	v_exp_f32_e32 v181, v68
	v_add_f32_e32 v66, v96, v66
	v_exp_f32_e32 v182, v69
	v_add_f32_e32 v66, v97, v66
	v_exp_f32_e32 v183, v70
	v_add_f32_e32 v66, v179, v66
	v_exp_f32_e32 v184, v71
	v_add_f32_e32 v66, v180, v66
	v_exp_f32_e32 v185, v72
	v_add_f32_e32 v66, v181, v66
	v_exp_f32_e32 v186, v73
	v_add_f32_e32 v66, v182, v66
	v_exp_f32_e32 v187, v74
	v_add_f32_e32 v66, v183, v66
	v_exp_f32_e32 v188, v75
	v_add_f32_e32 v66, v184, v66
	v_exp_f32_e32 v189, v76
	v_add_f32_e32 v66, v185, v66
	v_exp_f32_e32 v190, v77
	v_add_f32_e32 v66, v186, v66
	v_exp_f32_e32 v191, v78
	v_add_f32_e32 v66, v187, v66
	v_exp_f32_e32 v202, v79
	v_add_f32_e32 v66, v188, v66
	v_exp_f32_e32 v203, v80
	v_add_f32_e32 v66, v189, v66
	v_exp_f32_e32 v177, v177
	v_add_f32_e32 v66, v190, v66
	v_add_f32_e32 v66, v191, v66
	v_add_f32_e32 v66, v202, v66
	v_add_f32_e32 v66, v203, v66
	v_add_f32_e32 v83, v177, v66
	v_mov_b32_e32 v84, v83
	v_cvt_pk_bf16_f32 v66, v81, v176
	v_cvt_pk_bf16_f32 v67, v178, v85
	v_cvt_pk_bf16_f32 v68, v86, v87
	v_cvt_pk_bf16_f32 v69, v88, v89
	v_cvt_pk_bf16_f32 v70, v90, v91
	v_cvt_pk_bf16_f32 v71, v92, v93
	v_cvt_pk_bf16_f32 v72, v94, v95
	v_cvt_pk_bf16_f32 v73, v96, v97
	v_cvt_pk_bf16_f32 v74, v179, v180
	v_cvt_pk_bf16_f32 v75, v181, v182
	v_cvt_pk_bf16_f32 v76, v183, v184
	v_cvt_pk_bf16_f32 v77, v185, v186
	v_cvt_pk_bf16_f32 v78, v187, v188
	v_cvt_pk_bf16_f32 v79, v189, v190
	v_cvt_pk_bf16_f32 v80, v191, v202
	v_cvt_pk_bf16_f32 v81, v203, v177
	v_permlane32_swap_b32_e32 v83, v84
	v_permlane32_swap_b32_e32 v66, v68
	v_permlane32_swap_b32_e32 v67, v69
	v_permlane32_swap_b32_e32 v70, v72
	v_permlane32_swap_b32_e32 v71, v73
	v_permlane32_swap_b32_e32 v74, v76
	v_permlane32_swap_b32_e32 v75, v77
	v_permlane32_swap_b32_e32 v78, v80
	v_permlane32_swap_b32_e32 v79, v81
	v_cmp_gt_f32_e32 vcc, 1.0, v82
	s_cbranch_vccz .LBB0_287
	s_and_saveexec_b64 vcc, s[38:39]
	s_cbranch_execz .LBB0_286
	ds_write_b32 v151, v82 offset:128
	s_branch .LBB0_286

; #define SLOAD(i, k0) do { sr_[i].vs0 = *(const bf16x8*)(&Vh[(long)((k0) + sr) * LDK + sc]); sr_[i].vs1 = *(const bf16x8*)(&Vh[(long)((k0) + 32 + sr) * LDK + sc]); \
;     sr_[i].ks0 = *(const bf16x8*)(&Kh[(long)((k0) + sr) * LDK + sc]); sr_[i].ks1 = *(const bf16x8*)(&Kh[(long)((k0) + 32 + sr) * LDK + sc]); } while (0)
; #define SWRITE(b, i) do { *(bf16x8*)(V_lds + (b) * SHM_V + vst0) = sr_[i].vs0;          \
;     *(bf16x8*)(V_lds + (b) * SHM_V + vst1) = sr_[i].vs1; int kc = sc * 2;               \
;     *(bf16x8*)(K_lds + (b) * SHM_K + KSWZ(sr, kc)) = sr_[i].ks0;                       \
;     *(bf16x8*)(K_lds + (b) * SHM_K + KSWZ(32 + sr, kc)) = sr_[i].ks1; } while (0)
; template <int MODE, int SDEPTH, bool SIMPLE>
; __device__ __forceinline__ void attn_body(const Unit& U, char* lds, const int tid) {
;     ...
;     for (int j = 0; j < NT; ++j) {
;       asm volatile("s_waitcnt vmcnt(0)" ::: "memory"); __syncthreads(); SWRITE(0, 0);
;       if (j + 1 < NT) SLOAD(0, (j + 1) * KVBLK);
;     ...
;       if constexpr (MODE == 2) { const int q0 = U.i0 + wid * 32, t0 = U.k0 + j * 64; act = (t0 + 63 >= q0 - 64) && (t0 <= q0 + 31 + 64); }
.LBB0_305:
	s_or_b64 exec, exec, s[0:1]
	s_add_i32 s42, s42, 64
	v_lshl_add_u64 v[150:151], v[150:151], 0, s[28:29]
	s_cmp_eq_u32 s39, s43
	v_lshl_add_u64 v[152:153], v[152:153], 0, s[28:29]
	s_cbranch_scc1 .LBB0_312
	.p2align	6

; __device__ __forceinline__ int crow(int r, int hi) { return (r & 3) + 8 * (r >> 2) + 4 * hi; }
; template <int MODE>
; __device__ __forceinline__ void amask(f32x16& p0, f32x16& p1, int j, const Unit& U, int wid, int r32, int hi, const float* tbl) {
;     ...
;     const int base = U.k0 + j * 64 - (U.i0 + wid * 32 + r32);
; #pragma unroll
;     for (int r = 0; r < 16; ++r) { const int c = crow(r, hi); const int d0 = abs(base + c), d1 = abs(base + c + 32);
;       p0[r] = (d0 <= 64) ? p0[r] - U.slope * (float)d0 : NEG;
;       p1[r] = (d1 <= 64) ? p1[r] - U.slope * (float)d1 : NEG; }
; template <int MODE, int SDEPTH, bool SIMPLE>
; __device__ __forceinline__ void attn_body(const Unit& U, char* lds, const int tid) {
;     ...
;       if constexpr (MODE == 2) { const int q0 = U.i0 + wid * 32, t0 = U.k0 + j * 64; act = (t0 + 63 >= q0 - 64) && (t0 <= q0 + 31 + 64); }
;       if (act) {
;         qkt(p0, p1, K_lds, qr, r32, hi); amask<MODE>(p0, p1, j, U, wid, r32, hi, tbl);
.LBB0_308:
	s_add_i32 s0, s40, s42
	s_add_i32 s1, s0, 63
	v_cmp_ge_i32_e32 vcc, s1, v162
	v_cmp_le_i32_e64 s[0:1], s0, v163
	s_and_b64 s[2:3], vcc, s[0:1]
	s_waitcnt lgkmcnt(0)
	s_barrier
	s_and_saveexec_b64 s[0:1], s[2:3]
	s_cbranch_execz .LBB0_305
	ds_read_b128 v[66:69], v170 offset:32768
	ds_read_b128 v[70:73], v170 offset:40960
	ds_read_b128 v[178:181], v171 offset:32768
	ds_read_b128 v[182:185], v171 offset:40960
	s_waitcnt lgkmcnt(3)
	v_mfma_f32_32x32x16_bf16 v[82:97], v[66:69], v[122:125], 0
	s_waitcnt lgkmcnt(2)
	v_mfma_f32_32x32x16_bf16 v[66:81], v[70:73], v[122:125], 0
	s_waitcnt lgkmcnt(1)
	v_mfma_f32_32x32x16_bf16 v[82:97], v[178:181], v[98:101], v[82:97]
	s_waitcnt lgkmcnt(0)
	v_mfma_f32_32x32x16_bf16 v[66:81], v[182:185], v[98:101], v[66:81]
	ds_read_b128 v[178:181], v172 offset:32768
	ds_read_b128 v[182:185], v172 offset:40960
	s_waitcnt lgkmcnt(1)
	v_mfma_f32_32x32x16_bf16 v[82:97], v[178:181], v[102:105], v[82:97]
	s_waitcnt lgkmcnt(0)
	v_mfma_f32_32x32x16_bf16 v[66:81], v[182:185], v[102:105], v[66:81]
	ds_read_b128 v[178:181], v173 offset:32768
	ds_read_b128 v[182:185], v173 offset:40960
	s_waitcnt lgkmcnt(1)
	v_mfma_f32_32x32x16_bf16 v[82:97], v[178:181], v[106:109], v[82:97]
	s_waitcnt lgkmcnt(0)
	v_mfma_f32_32x32x16_bf16 v[66:81], v[182:185], v[106:109], v[66:81]
	ds_read_b128 v[178:181], v174 offset:32768
	ds_read_b128 v[182:185], v174 offset:40960
	s_waitcnt lgkmcnt(1)
	v_mfma_f32_32x32x16_bf16 v[82:97], v[178:181], v[110:113], v[82:97]
	s_waitcnt lgkmcnt(0)
	v_mfma_f32_32x32x16_bf16 v[66:81], v[182:185], v[110:113], v[66:81]
	ds_read_b128 v[178:181], v175 offset:32768
	ds_read_b128 v[182:185], v175 offset:40960
	s_waitcnt lgkmcnt(1)
	v_mfma_f32_32x32x16_bf16 v[82:97], v[178:181], v[114:117], v[82:97]
	s_waitcnt lgkmcnt(0)
	v_mfma_f32_32x32x16_bf16 v[66:81], v[182:185], v[114:117], v[66:81]
	ds_read_b128 v[178:181], v176 offset:32768
	ds_read_b128 v[182:185], v176 offset:40960
	s_waitcnt lgkmcnt(1)
	v_mfma_f32_32x32x16_bf16 v[82:97], v[178:181], v[118:121], v[82:97]
	s_waitcnt lgkmcnt(0)
	v_mfma_f32_32x32x16_bf16 v[66:81], v[182:185], v[118:121], v[66:81]
	ds_read_b128 v[178:181], v177 offset:32768
	ds_read_b128 v[182:185], v177 offset:40960
	s_waitcnt lgkmcnt(1)
	v_mfma_f32_32x32x16_bf16 v[82:97], v[178:181], v[126:129], v[82:97]
	v_add_u32_e32 v178, s42, v164
	v_sub_u32_e32 v179, 0, v178
	v_max_i32_e32 v179, v178, v179
	v_cmp_gt_u32_e32 vcc, s13, v179
	v_cvt_f32_u32_e32 v179, v179
	v_add_u32_e32 v180, 32, v178
	v_sub_u32_e32 v181, 0xffffffe0, v178
	s_waitcnt lgkmcnt(0)
	v_mfma_f32_32x32x16_bf16 v[66:81], v[182:185], v[126:129], v[66:81]
	v_max_i32_e32 v180, v180, v181
	s_nop 1
	v_fma_f32 v82, -v65, v179, v82
	v_cvt_f32_u32_e32 v179, v180
	v_cndmask_b32_e32 v82, v230, v82, vcc
	v_cmp_gt_u32_e32 vcc, s13, v180
	v_not_b32_e32 v180, v178
	v_sub_u32_e32 v181, 0xffffffdf, v178
	s_nop 2
	v_fma_f32 v66, -v65, v179, v66
	v_add_u32_e32 v179, 1, v178
	v_max_i32_e32 v179, v179, v180
	v_cndmask_b32_e32 v66, v230, v66, vcc
	v_cmp_gt_u32_e32 vcc, s13, v179
	v_cvt_f32_u32_e32 v179, v179
	v_add_u32_e32 v180, 33, v178
	v_max_i32_e32 v180, v180, v181
	v_sub_u32_e32 v181, 0xffffffde, v178
	v_fma_f32 v83, -v65, v179, v83
	v_cvt_f32_u32_e32 v179, v180
	v_cndmask_b32_e32 v83, v230, v83, vcc
	v_cmp_gt_u32_e32 vcc, s13, v180
	v_sub_u32_e32 v180, -2, v178
	v_fma_f32 v67, -v65, v179, v67
	v_add_u32_e32 v179, 2, v178
	v_max_i32_e32 v179, v179, v180
	v_cndmask_b32_e32 v67, v230, v67, vcc
	v_cmp_gt_u32_e32 vcc, s13, v179
	v_cvt_f32_u32_e32 v179, v179
	v_add_u32_e32 v180, 34, v178
	v_max_i32_e32 v180, v180, v181
	v_sub_u32_e32 v181, 0xffffffdd, v178
	v_fma_f32 v84, -v65, v179, v84
	v_cvt_f32_u32_e32 v179, v180
	v_cndmask_b32_e32 v84, v230, v84, vcc
	v_cmp_gt_u32_e32 vcc, s13, v180
	v_sub_u32_e32 v180, -3, v178
	v_fma_f32 v68, -v65, v179, v68
	v_add_u32_e32 v179, 3, v178
	v_max_i32_e32 v179, v179, v180
	v_cndmask_b32_e32 v68, v230, v68, vcc
	v_cmp_gt_u32_e32 vcc, s13, v179
	v_cvt_f32_u32_e32 v179, v179
	v_add_u32_e32 v180, 35, v178
	v_max_i32_e32 v180, v180, v181
	v_sub_u32_e32 v181, 0xffffffd8, v178
	v_fma_f32 v85, -v65, v179, v85
	v_cvt_f32_u32_e32 v179, v180
	v_cndmask_b32_e32 v85, v230, v85, vcc
	v_cmp_gt_u32_e32 vcc, s13, v180
	v_sub_u32_e32 v180, -8, v178
	v_fma_f32 v69, -v65, v179, v69
	v_add_u32_e32 v179, 8, v178
	v_max_i32_e32 v179, v179, v180
	v_cndmask_b32_e32 v69, v230, v69, vcc
	v_cmp_gt_u32_e32 vcc, s13, v179
	v_cvt_f32_u32_e32 v179, v179
	v_add_u32_e32 v180, 40, v178
	v_max_i32_e32 v180, v180, v181
	v_sub_u32_e32 v181, 0xffffffd7, v178
	v_fma_f32 v86, -v65, v179, v86
	v_cvt_f32_u32_e32 v179, v180
	v_cndmask_b32_e32 v86, v230, v86, vcc
	v_cmp_gt_u32_e32 vcc, s13, v180
	v_sub_u32_e32 v180, -9, v178
	v_fma_f32 v70, -v65, v179, v70
	v_add_u32_e32 v179, 9, v178
	v_max_i32_e32 v179, v179, v180
	v_cndmask_b32_e32 v70, v230, v70, vcc
	v_cmp_gt_u32_e32 vcc, s13, v179
	v_cvt_f32_u32_e32 v179, v179
	v_add_u32_e32 v180, 41, v178
	v_max_i32_e32 v180, v180, v181
	v_sub_u32_e32 v181, 0xffffffd6, v178
	v_fma_f32 v87, -v65, v179, v87
	v_cvt_f32_u32_e32 v179, v180
	v_cndmask_b32_e32 v87, v230, v87, vcc
	v_cmp_gt_u32_e32 vcc, s13, v180
	v_sub_u32_e32 v180, -10, v178
	v_fma_f32 v71, -v65, v179, v71
	v_add_u32_e32 v179, 10, v178
	v_max_i32_e32 v179, v179, v180
	v_cndmask_b32_e32 v71, v230, v71, vcc
	v_cmp_gt_u32_e32 vcc, s13, v179
	v_cvt_f32_u32_e32 v179, v179
	v_add_u32_e32 v180, 42, v178
	v_max_i32_e32 v180, v180, v181
	v_sub_u32_e32 v181, 0xffffffd5, v178
	v_fma_f32 v88, -v65, v179, v88
	v_cvt_f32_u32_e32 v179, v180
	v_cndmask_b32_e32 v88, v230, v88, vcc
	v_cmp_gt_u32_e32 vcc, s13, v180
	v_sub_u32_e32 v180, -11, v178
	v_fma_f32 v72, -v65, v179, v72
; __device__ __forceinline__ int crow(int r, int hi) { return (r & 3) + 8 * (r >> 2) + 4 * hi; }
; __device__ __forceinline__ void partialSM(f32x16& p0, f32x16& p1, float& m_reg, float& mn, float& alpha) {
;     ...
;   float pmax = p0[0];
; #pragma unroll
;   for (int r = 1; r < 16; ++r) pmax = fmaxf(pmax, p0[r]);
; #pragma unroll
;   for (int r = 0; r < 16; ++r) pmax = fmaxf(pmax, p1[r]);
; template <int MODE>
; __device__ __forceinline__ void amask(f32x16& p0, f32x16& p1, int j, const Unit& U, int wid, int r32, int hi, const float* tbl) {
;     ...
;     const int base = U.k0 + j * 64 - (U.i0 + wid * 32 + r32);
; #pragma unroll
;     for (int r = 0; r < 16; ++r) { const int c = crow(r, hi); const int d0 = abs(base + c), d1 = abs(base + c + 32);
;       p0[r] = (d0 <= 64) ? p0[r] - U.slope * (float)d0 : NEG;
;       p1[r] = (d1 <= 64) ? p1[r] - U.slope * (float)d1 : NEG; }
	v_add_u32_e32 v179, 11, v178
	v_max_i32_e32 v179, v179, v180
	v_cndmask_b32_e32 v72, v230, v72, vcc
	v_cmp_gt_u32_e32 vcc, s13, v179
	v_cvt_f32_u32_e32 v179, v179
	v_add_u32_e32 v180, 43, v178
	v_max_i32_e32 v180, v180, v181
	v_sub_u32_e32 v181, 0xffffffd0, v178
	v_fma_f32 v89, -v65, v179, v89
	v_cvt_f32_u32_e32 v179, v180
	v_cndmask_b32_e32 v89, v230, v89, vcc
	v_cmp_gt_u32_e32 vcc, s13, v180
	v_sub_u32_e32 v180, -16, v178
	v_fma_f32 v73, -v65, v179, v73
	v_add_u32_e32 v179, 16, v178
	v_max_i32_e32 v179, v179, v180
	v_cndmask_b32_e32 v73, v230, v73, vcc
	v_cmp_gt_u32_e32 vcc, s13, v179
	v_cvt_f32_u32_e32 v179, v179
	v_add_u32_e32 v180, 48, v178
	v_max_i32_e32 v180, v180, v181
	v_sub_u32_e32 v181, 0xffffffcf, v178
	v_fma_f32 v90, -v65, v179, v90
	v_cvt_f32_u32_e32 v179, v180
	v_cndmask_b32_e32 v90, v230, v90, vcc
	v_cmp_gt_u32_e32 vcc, s13, v180
	v_sub_u32_e32 v180, 0xffffffef, v178
	v_fma_f32 v74, -v65, v179, v74
	v_add_u32_e32 v179, 17, v178
	v_max_i32_e32 v179, v179, v180
	v_cndmask_b32_e32 v74, v230, v74, vcc
	v_cmp_gt_u32_e32 vcc, s13, v179
	v_cvt_f32_u32_e32 v179, v179
	v_add_u32_e32 v180, 49, v178
	v_max_i32_e32 v180, v180, v181
	v_sub_u32_e32 v181, 0xffffffce, v178
	v_fma_f32 v91, -v65, v179, v91
	v_cndmask_b32_e32 v179, v230, v91, vcc
	v_cvt_f32_u32_e32 v91, v180
	v_cmp_gt_u32_e32 vcc, s13, v180
	v_sub_u32_e32 v180, 0xffffffee, v178
	v_fma_f32 v75, -v65, v91, v75
	v_add_u32_e32 v91, 18, v178
	v_max_i32_e32 v91, v91, v180
	v_cndmask_b32_e32 v75, v230, v75, vcc
	v_cmp_gt_u32_e32 vcc, s13, v91
	v_cvt_f32_u32_e32 v91, v91
	v_add_u32_e32 v180, 50, v178
	v_max_i32_e32 v180, v180, v181
	v_sub_u32_e32 v181, 0xffffffcd, v178
	v_fma_f32 v91, -v65, v91, v92
	v_cndmask_b32_e32 v92, v230, v91, vcc
	v_cvt_f32_u32_e32 v91, v180
	v_cmp_gt_u32_e32 vcc, s13, v180
	v_sub_u32_e32 v180, 0xffffffed, v178
	v_fma_f32 v76, -v65, v91, v76
	v_add_u32_e32 v91, 19, v178
	v_max_i32_e32 v91, v91, v180
	v_cndmask_b32_e32 v76, v230, v76, vcc
	v_cmp_gt_u32_e32 vcc, s13, v91
	v_cvt_f32_u32_e32 v91, v91
	v_add_u32_e32 v180, 51, v178
	v_max_i32_e32 v180, v180, v181
	v_sub_u32_e32 v181, 0xffffffc8, v178
	v_fma_f32 v91, -v65, v91, v93
	v_cndmask_b32_e32 v93, v230, v91, vcc
	v_cvt_f32_u32_e32 v91, v180
	v_cmp_gt_u32_e32 vcc, s13, v180
	v_sub_u32_e32 v180, 0xffffffe8, v178
	v_fma_f32 v77, -v65, v91, v77
	v_add_u32_e32 v91, 24, v178
	v_max_i32_e32 v91, v91, v180
	v_cndmask_b32_e32 v77, v230, v77, vcc
	v_cmp_gt_u32_e32 vcc, s13, v91
	v_cvt_f32_u32_e32 v91, v91
	v_add_u32_e32 v180, 56, v178
	v_max_i32_e32 v180, v180, v181
	v_sub_u32_e32 v181, 0xffffffc7, v178
	v_fma_f32 v91, -v65, v91, v94
	v_cndmask_b32_e32 v94, v230, v91, vcc
	v_cvt_f32_u32_e32 v91, v180
	v_cmp_gt_u32_e32 vcc, s13, v180
	v_sub_u32_e32 v180, 0xffffffe7, v178
	v_fma_f32 v78, -v65, v91, v78
	v_add_u32_e32 v91, 25, v178
	v_max_i32_e32 v91, v91, v180
	v_cndmask_b32_e32 v78, v230, v78, vcc
	v_cmp_gt_u32_e32 vcc, s13, v91
	v_cvt_f32_u32_e32 v91, v91
	v_add_u32_e32 v180, 57, v178
	v_max_i32_e32 v180, v180, v181
	v_sub_u32_e32 v181, 0xffffffc6, v178
	v_fma_f32 v91, -v65, v91, v95
	v_cndmask_b32_e32 v95, v230, v91, vcc
	v_cvt_f32_u32_e32 v91, v180
	v_cmp_gt_u32_e32 vcc, s13, v180
	v_sub_u32_e32 v180, 0xffffffe6, v178
	v_fma_f32 v79, -v65, v91, v79
	v_add_u32_e32 v91, 26, v178
	v_max_i32_e32 v91, v91, v180
	v_cndmask_b32_e32 v79, v230, v79, vcc
	v_cmp_gt_u32_e32 vcc, s13, v91
	v_cvt_f32_u32_e32 v91, v91
	v_add_u32_e32 v180, 58, v178
	v_max_i32_e32 v180, v180, v181
	v_fma_f32 v91, -v65, v91, v96
	v_cndmask_b32_e32 v96, v230, v91, vcc
	v_cvt_f32_u32_e32 v91, v180
	v_cmp_gt_u32_e32 vcc, s13, v180
	v_sub_u32_e32 v180, 0xffffffe5, v178
	v_fma_f32 v80, -v65, v91, v80
	v_add_u32_e32 v91, 27, v178
	v_max_i32_e32 v91, v91, v180
	v_cndmask_b32_e32 v80, v230, v80, vcc
	v_cmp_gt_u32_e32 vcc, s13, v91
	v_cvt_f32_u32_e32 v91, v91
	v_add_u32_e32 v180, 59, v178
	v_sub_u32_e32 v178, 0xffffffc5, v178
	v_max_i32_e32 v178, v180, v178
	v_fma_f32 v91, -v65, v91, v97
	v_cndmask_b32_e32 v97, v230, v91, vcc
	v_cvt_f32_u32_e32 v91, v178
	v_cmp_gt_u32_e32 vcc, s13, v178
	v_fma_f32 v81, -v65, v91, v81
	v_max_f32_e32 v91, v82, v83
	v_max3_f32 v91, v91, v84, v85
	v_max3_f32 v91, v91, v86, v87
	v_max3_f32 v91, v91, v88, v89
	v_max3_f32 v91, v91, v90, v179
	v_max3_f32 v91, v91, v92, v93
	v_max3_f32 v91, v91, v94, v95
	v_max3_f32 v91, v91, v96, v97
	v_max3_f32 v91, v91, v66, v67
	v_max3_f32 v91, v91, v68, v69
	v_max3_f32 v91, v91, v70, v71
	v_max3_f32 v91, v91, v72, v73
	v_max3_f32 v91, v91, v74, v75
	v_max3_f32 v91, v91, v76, v77
	v_cndmask_b32_e32 v81, v230, v81, vcc
; __device__ __forceinline__ void partialSM(f32x16& p0, f32x16& p1, float& m_reg, float& mn, float& alpha) {
;     ...
;   { auto rr = __builtin_amdgcn_permlane32_swap(__float_as_uint(pmax), __float_as_uint(pmax), false, false);
;     pmax = fmaxf(__uint_as_float(rr[0]), __uint_as_float(rr[1])); }
;   if (__builtin_expect(__all(pmax - m_reg <= THR / SCALE), 1)) { mn = m_reg; alpha = 1.f; }
;   else { mn = fmaxf(m_reg, pmax); alpha = __builtin_amdgcn_exp2f((m_reg - mn) * C); m_reg = mn; }
;   float mnC = -mn * C;
; #pragma unroll
;   for (int r = 0; r < 16; ++r) p0[r] = fmaf(p0[r], C, mnC);
; #pragma unroll
;   for (int r = 0; r < 16; ++r) p1[r] = fmaf(p1[r], C, mnC);
; #pragma unroll
;   for (int r = 0; r < 16; ++r) p0[r] = __builtin_amdgcn_exp2f(p0[r]);
; }
; __device__ __forceinline__ void finishSM(f32x16& p0, f32x16& p1, float alpha, float& l_reg, bf16x8& pa0, bf16x8& pa1, bf16x8& pa2, bf16x8& pa3) {
; #pragma unroll
;   for (int r = 0; r < 16; ++r) p1[r] = __builtin_amdgcn_exp2f(p1[r]);
;   float ps = 0;
; #pragma unroll
;   for (int r = 0; r < 16; ++r) ps += p0[r];
; #pragma unroll
;   for (int r = 0; r < 16; ++r) ps += p1[r];
;   { auto rr = __builtin_amdgcn_permlane32_swap(__float_as_uint(ps), __float_as_uint(ps), false, false);
;     ps = __uint_as_float(rr[0]) + __uint_as_float(rr[1]); }
;   l_reg = l_reg * alpha + ps;
;     ...
;   PK4(p0, 0, pa0); PK4(p0, 8, pa1); PK4(p1, 0, pa2); PK4(p1, 8, pa3);
	v_max3_f32 v91, v91, v78, v79
	v_max3_f32 v91, v91, v80, v81
	v_mov_b32_e32 v178, v91
	s_nop 1
	v_permlane32_swap_b32_e32 v91, v178
	v_max_f32_e32 v91, v91, v178
	v_sub_f32_e32 v178, v91, v165
	v_cmp_ge_f32_e32 vcc, s18, v178
	v_max_f32_e32 v91, v165, v91
	v_sub_f32_e32 v178, v165, v91
	v_mul_f32_e32 v178, 0x3e0293ee, v178
	v_exp_f32_e32 v178, v178
	s_cmp_eq_u64 vcc, exec
	s_cselect_b64 vcc, -1, 0
	v_cndmask_b32_e32 v165, v91, v165, vcc
	v_cndmask_b32_e64 v91, v178, 1.0, vcc
	v_mul_f32_e32 v178, 0xbe0293ee, v165
	v_fmamk_f32 v82, v82, 0x3e0293ee, v178
	v_fmamk_f32 v83, v83, 0x3e0293ee, v178
	v_fmamk_f32 v84, v84, 0x3e0293ee, v178
	v_fmamk_f32 v85, v85, 0x3e0293ee, v178
	v_fmamk_f32 v86, v86, 0x3e0293ee, v178
	v_fmamk_f32 v87, v87, 0x3e0293ee, v178
	v_fmamk_f32 v88, v88, 0x3e0293ee, v178
	v_fmamk_f32 v89, v89, 0x3e0293ee, v178
	v_fmamk_f32 v90, v90, 0x3e0293ee, v178
	v_fmamk_f32 v179, v179, 0x3e0293ee, v178
	v_fmamk_f32 v92, v92, 0x3e0293ee, v178
	v_fmamk_f32 v93, v93, 0x3e0293ee, v178
	v_fmamk_f32 v94, v94, 0x3e0293ee, v178
	v_fmamk_f32 v95, v95, 0x3e0293ee, v178
	v_fmamk_f32 v96, v96, 0x3e0293ee, v178
	v_fmamk_f32 v97, v97, 0x3e0293ee, v178
	v_fmamk_f32 v66, v66, 0x3e0293ee, v178
	v_fmamk_f32 v67, v67, 0x3e0293ee, v178
	v_fmamk_f32 v68, v68, 0x3e0293ee, v178
	v_fmamk_f32 v69, v69, 0x3e0293ee, v178
	v_fmamk_f32 v70, v70, 0x3e0293ee, v178
	v_fmamk_f32 v71, v71, 0x3e0293ee, v178
	v_fmamk_f32 v72, v72, 0x3e0293ee, v178
	v_fmamk_f32 v73, v73, 0x3e0293ee, v178
	v_fmamk_f32 v74, v74, 0x3e0293ee, v178
	v_fmamk_f32 v75, v75, 0x3e0293ee, v178
	v_fmamk_f32 v76, v76, 0x3e0293ee, v178
	v_fmamk_f32 v77, v77, 0x3e0293ee, v178
	v_fmamk_f32 v78, v78, 0x3e0293ee, v178
	v_fmamk_f32 v79, v79, 0x3e0293ee, v178
	v_fmamk_f32 v80, v80, 0x3e0293ee, v178
	v_fmac_f32_e32 v178, 0x3e0293ee, v81
	v_exp_f32_e32 v81, v82
	v_exp_f32_e32 v180, v83
	v_exp_f32_e32 v84, v84
	v_exp_f32_e32 v85, v85
	v_exp_f32_e32 v86, v86
	v_exp_f32_e32 v181, v66
	v_exp_f32_e32 v87, v87
	v_add_f32_e32 v66, v180, v81
	v_exp_f32_e32 v88, v88
	v_add_f32_e32 v66, v84, v66
	v_exp_f32_e32 v89, v89
	v_add_f32_e32 v66, v85, v66
	v_exp_f32_e32 v90, v90
	v_add_f32_e32 v66, v86, v66
	v_exp_f32_e32 v179, v179
	v_add_f32_e32 v66, v87, v66
	v_exp_f32_e32 v92, v92
	v_add_f32_e32 v66, v88, v66
	v_exp_f32_e32 v93, v93
	v_add_f32_e32 v66, v89, v66
	v_exp_f32_e32 v94, v94
	v_add_f32_e32 v66, v90, v66
	v_exp_f32_e32 v95, v95
	v_add_f32_e32 v66, v179, v66
	v_exp_f32_e32 v96, v96
	v_add_f32_e32 v66, v92, v66
	v_exp_f32_e32 v97, v97
	v_add_f32_e32 v66, v93, v66
	v_add_f32_e32 v66, v94, v66
	v_exp_f32_e32 v182, v67
	v_add_f32_e32 v66, v95, v66
	v_exp_f32_e32 v183, v68
	v_add_f32_e32 v66, v96, v66
	v_exp_f32_e32 v184, v69
	v_add_f32_e32 v66, v97, v66
	v_exp_f32_e32 v185, v70
	v_add_f32_e32 v66, v181, v66
	v_exp_f32_e32 v186, v71
	v_add_f32_e32 v66, v182, v66
	v_exp_f32_e32 v187, v72
	v_add_f32_e32 v66, v183, v66
	v_exp_f32_e32 v188, v73
	v_add_f32_e32 v66, v184, v66
	v_exp_f32_e32 v189, v74
	v_add_f32_e32 v66, v185, v66
	v_exp_f32_e32 v190, v75
	v_add_f32_e32 v66, v186, v66
	v_exp_f32_e32 v191, v76
	v_add_f32_e32 v66, v187, v66
	v_exp_f32_e32 v202, v77
	v_add_f32_e32 v66, v188, v66
	v_exp_f32_e32 v203, v78
	v_add_f32_e32 v66, v189, v66
	v_exp_f32_e32 v204, v79
	v_add_f32_e32 v66, v190, v66
	v_exp_f32_e32 v205, v80
	v_add_f32_e32 v66, v191, v66
	v_exp_f32_e32 v178, v178
	v_add_f32_e32 v66, v202, v66
	v_add_f32_e32 v66, v203, v66
	v_add_f32_e32 v66, v204, v66
	v_add_f32_e32 v66, v205, v66
	v_add_f32_e32 v82, v178, v66
	v_mov_b32_e32 v83, v82
	v_cvt_pk_bf16_f32 v66, v81, v180
	v_cvt_pk_bf16_f32 v67, v84, v85
	v_cvt_pk_bf16_f32 v68, v86, v87
	v_cvt_pk_bf16_f32 v69, v88, v89
	v_cvt_pk_bf16_f32 v70, v90, v179
	v_cvt_pk_bf16_f32 v71, v92, v93
	v_cvt_pk_bf16_f32 v72, v94, v95
	v_cvt_pk_bf16_f32 v73, v96, v97
	v_cvt_pk_bf16_f32 v74, v181, v182
	v_cvt_pk_bf16_f32 v75, v183, v184
	v_cvt_pk_bf16_f32 v76, v185, v186
	v_cvt_pk_bf16_f32 v77, v187, v188
	v_cvt_pk_bf16_f32 v78, v189, v190
	v_cvt_pk_bf16_f32 v79, v191, v202
	v_cvt_pk_bf16_f32 v80, v203, v204
	v_cvt_pk_bf16_f32 v81, v205, v178
	v_permlane32_swap_b32_e32 v82, v83
	v_permlane32_swap_b32_e32 v66, v68
	v_permlane32_swap_b32_e32 v67, v69
	v_permlane32_swap_b32_e32 v70, v72
	v_permlane32_swap_b32_e32 v71, v73
	v_permlane32_swap_b32_e32 v74, v76
	v_permlane32_swap_b32_e32 v75, v77
	v_permlane32_swap_b32_e32 v78, v80
	v_permlane32_swap_b32_e32 v79, v81
	v_cmp_gt_f32_e32 vcc, 1.0, v91
	s_cbranch_vccz .LBB0_304
	s_and_saveexec_b64 s[2:3], s[36:37]
	s_cbranch_execz .LBB0_303
	ds_write_b32 v159, v91 offset:128
	s_branch .LBB0_303

; template <class Epi, class Sched>
; __device__ __forceinline__ void gemm_phase(LAS unsigned char* lds, const Gemm g, const Sched& S, const Epi& E, const int tid) {
;     ...
;         const bool has_next = S.next(ui + 1, nxt);
;         const char* nA = has_next ? (const char*)g.A + (size_t)nxt.pm * tstepA : cA; const char* nB = has_next ? (const char*)g.Bt + (size_t)nxt.pn * tstepB : cB;
;         for (int t = 0; t < nt; t += 2) {
;             const bool last = (t == nt - 2);
;             const char* a1 = cA + (size_t)(t + 1) * kstep;
;             const char* a2 = last ? nA : cA + (size_t)(t + 2) * kstep; const char* b2 = last ? nB : cB + (size_t)(t + 2) * kstep;
;     ...
;         for (int a = 0; a < 2; ++a)
; #pragma unroll
;             for (int b = 0; b < 2; ++b)
; #pragma unroll
;                 for (int m = 0; m < 4; ++m)
; #pragma unroll
;                     for (int n = 0; n < 2; ++n) acc[a][b][m][n] = (f32x4){0.f, 0.f, 0.f, 0.f};
.LBB0_346:
	s_ashr_i32 s31, s30, 31
	s_lshl_b64 s[20:21], s[30:31], 20
	s_add_u32 s40, s27, s20
	s_addc_u32 s41, s28, s21
	s_and_b64 s[20:21], s[36:37], exec
	s_cselect_b32 s15, s41, s3
	s_cselect_b32 s16, s40, s2
	s_ashr_i32 s11, s10, 31
	s_lshl_b64 s[20:21], s[10:11], 20
	s_add_u32 s42, s50, s20
	s_addc_u32 s43, s51, s21
	s_and_b64 s[20:21], s[36:37], exec
	s_cselect_b32 s11, s43, s39
	s_cselect_b32 s19, s42, s38
	s_add_u32 s2, s2, 0x80080
	s_addc_u32 s3, s3, 0
	s_add_u32 s20, s38, 0x100
	v_mov_b32_e32 v0, 0
	s_addc_u32 s21, s39, 0
	s_mov_b32 s22, -2
	v_mov_b32_e32 v1, v0
	v_mov_b32_e32 v2, v0
	v_mov_b32_e32 v3, v0
	v_mov_b32_e32 v4, v0
	v_mov_b32_e32 v5, v0
	v_mov_b32_e32 v6, v0
	v_mov_b32_e32 v7, v0
	v_mov_b32_e32 v16, v0
	v_mov_b32_e32 v17, v0
	v_mov_b32_e32 v18, v0
	v_mov_b32_e32 v19, v0
	v_mov_b32_e32 v20, v0
	v_mov_b32_e32 v21, v0
	v_mov_b32_e32 v22, v0
	v_mov_b32_e32 v23, v0
	v_mov_b32_e32 v32, v0
	v_mov_b32_e32 v33, v0
	v_mov_b32_e32 v34, v0
	v_mov_b32_e32 v35, v0
	v_mov_b32_e32 v36, v0
	v_mov_b32_e32 v37, v0
	v_mov_b32_e32 v38, v0
	v_mov_b32_e32 v39, v0
	v_mov_b32_e32 v48, v0
	v_mov_b32_e32 v49, v0
	v_mov_b32_e32 v50, v0
	v_mov_b32_e32 v51, v0
	v_mov_b32_e32 v52, v0
	v_mov_b32_e32 v53, v0
	v_mov_b32_e32 v54, v0
	v_mov_b32_e32 v55, v0
	v_mov_b32_e32 v8, v0
	v_mov_b32_e32 v9, v0
	v_mov_b32_e32 v10, v0
	v_mov_b32_e32 v11, v0
	v_mov_b32_e32 v12, v0
	v_mov_b32_e32 v13, v0
	v_mov_b32_e32 v14, v0
	v_mov_b32_e32 v15, v0
	v_mov_b32_e32 v24, v0
	v_mov_b32_e32 v25, v0
	v_mov_b32_e32 v26, v0
	v_mov_b32_e32 v27, v0
	v_mov_b32_e32 v28, v0
	v_mov_b32_e32 v29, v0
	v_mov_b32_e32 v30, v0
	v_mov_b32_e32 v31, v0
	v_mov_b32_e32 v40, v0
	v_mov_b32_e32 v41, v0
	v_mov_b32_e32 v42, v0
	v_mov_b32_e32 v43, v0
	v_mov_b32_e32 v44, v0
	v_mov_b32_e32 v45, v0
	v_mov_b32_e32 v46, v0
	v_mov_b32_e32 v47, v0
	v_mov_b32_e32 v56, v0
	v_mov_b32_e32 v57, v0
	v_mov_b32_e32 v58, v0
	v_mov_b32_e32 v59, v0
	v_mov_b32_e32 v60, v0
	v_mov_b32_e32 v61, v0
	v_mov_b32_e32 v62, v0
	v_mov_b32_e32 v63, v0
	v_mov_b32_e32 v64, v0
	v_mov_b32_e32 v65, v0
	v_mov_b32_e32 v66, v0
	v_mov_b32_e32 v67, v0
	v_mov_b32_e32 v68, v0
	v_mov_b32_e32 v69, v0
	v_mov_b32_e32 v70, v0
	v_mov_b32_e32 v71, v0
	v_mov_b32_e32 v80, v0
	v_mov_b32_e32 v81, v0
	v_mov_b32_e32 v82, v0
	v_mov_b32_e32 v83, v0
	v_mov_b32_e32 v84, v0
	v_mov_b32_e32 v85, v0
	v_mov_b32_e32 v86, v0
	v_mov_b32_e32 v87, v0
	v_mov_b32_e32 v96, v0
	v_mov_b32_e32 v97, v0
	v_mov_b32_e32 v98, v0
	v_mov_b32_e32 v99, v0
	v_mov_b32_e32 v100, v0
	v_mov_b32_e32 v101, v0
	v_mov_b32_e32 v102, v0
	v_mov_b32_e32 v103, v0
	v_mov_b32_e32 v112, v0
	v_mov_b32_e32 v113, v0
	v_mov_b32_e32 v114, v0
	v_mov_b32_e32 v115, v0
	v_mov_b32_e32 v116, v0
	v_mov_b32_e32 v117, v0
	v_mov_b32_e32 v118, v0
	v_mov_b32_e32 v119, v0
	v_mov_b32_e32 v72, v0
	v_mov_b32_e32 v73, v0
	v_mov_b32_e32 v74, v0
	v_mov_b32_e32 v75, v0
	v_mov_b32_e32 v76, v0
	v_mov_b32_e32 v77, v0
	v_mov_b32_e32 v78, v0
	v_mov_b32_e32 v79, v0
	v_mov_b32_e32 v88, v0
	v_mov_b32_e32 v89, v0
	v_mov_b32_e32 v90, v0
	v_mov_b32_e32 v91, v0
	v_mov_b32_e32 v92, v0
	v_mov_b32_e32 v93, v0
	v_mov_b32_e32 v94, v0
	v_mov_b32_e32 v95, v0
	v_mov_b32_e32 v104, v0
	v_mov_b32_e32 v105, v0
	v_mov_b32_e32 v106, v0
	v_mov_b32_e32 v107, v0
	v_mov_b32_e32 v108, v0
	v_mov_b32_e32 v109, v0
	v_mov_b32_e32 v110, v0
	v_mov_b32_e32 v111, v0
	v_mov_b32_e32 v120, v0
	v_mov_b32_e32 v121, v0
	v_mov_b32_e32 v122, v0
	v_mov_b32_e32 v123, v0
	v_mov_b32_e32 v124, v0
	v_mov_b32_e32 v125, v0
	v_mov_b32_e32 v126, v0
	v_mov_b32_e32 v127, v0
	.p2align	6
